# band attention: one wave handles both 32-query halves of a chunk so each K/V tile DMA serves 64 queries (half the L2 traffic)
# speedup vs baseline: 1.0811x; 1.0109x over previous
; #define LAS __attribute__((address_space(3)))
; DI void p0_prep(const Params& p, LAS unsigned char* lds) {
;     int tid = threadIdx.x; asm volatile("" : "+v"(tid));
;     const int lane = tid & 63, wid = __builtin_amdgcn_readfirstlane(tid >> 6);
;     const int gw = blockIdx.x * 8 + wid, NGW = gridDim.x * 8;
;     unsigned char* ws = p.ws;
;     LAS float* scr = (LAS float*)(lds + wid * 8448);
;     constexpr int J1 = 28 * 128, J2 = J1 + 256, J3 = J2 + 256, J4 = J3 + 256, J5 = J4 + 128, J6 = J5 + 512;
;     for (int it = gw; it < J6; it += NGW) {
;         if (it < J1) {
;             int t = it >> 7; const int rem = it & 127, g = rem >> 4, kb = rem & 15; if (t >= 12) t += 1;
;             const bool sw = (t == 4 || t == 5 || t == 10 || t == 11);
;             const int src = (t < 12 ? 256 * t : 256 * (t - 1) + 16) + 32 * (sw ? g : lgrp(g));
;             transpose_item(p.w_in + (size_t)(64 * kb) * 7184 + src, 7184, (bf16_t*)(ws + OFF_WINT) + (size_t)(t * 256 + 32 * g) * 1024 + 64 * kb, 1024, scr, lane);
; __global__ void __launch_bounds__(512, 2) fwd_megakernel(Params p) {
;     extern __shared__ __attribute__((aligned(16))) unsigned char lds_raw[];
;     LAS unsigned char* lds = (LAS unsigned char*)lds_raw;
;     if (threadIdx.x < 4) ((volatile LAS unsigned*)(lds + LDS_BAR))[threadIdx.x] = 0u;
;     __syncthreads();
;     const XcdBarrier bar = xcd_barrier_post((unsigned*)(p.ws + OFF_BAR), (volatile LAS unsigned*)(lds + LDS_BAR));
;     if (p.ws == nullptr) cg::this_grid().sync();
;     p0_prep(p, lds);
.LBB0_18:
	s_or_b64 exec, exec, s[4:5]
	s_getpc_b64 s[100:101]
	s_lshr_b32 s4, s2, 3
	s_lshl_b32 s4, s4, 13
	v_lshlrev_b32_e32 v168, 4, v203
	v_add_u32_e32 v168, s4, v168
	v_cmp_gt_u32_e32 vcc, 0x27a00, v168
	s_and_saveexec_b64 s[4:5], vcc
	global_load_dwordx4 v[172:175], v168, s[100:101]
	s_or_b64 exec, exec, s[4:5]
	v_mov_b32_e32 v87, v203
	s_lshl_b32 s49, s2, 3
	v_readfirstlane_b32 s3, v87
	s_ashr_i32 s8, s3, 6
	s_load_dword s3, s[0:1], 0xd0
	s_add_i32 s20, s8, s49
	s_add_u32 s4, s0, 0xd0
	s_addc_u32 s5, s1, 0
	v_and_b32_e32 v1, 63, v87
	v_writelane_b32 v255, s4, 2
	s_waitcnt lgkmcnt(0)
	s_lshl_b32 s74, s3, 3
	s_cmpk_gt_i32 s20, 0x137f
	v_writelane_b32 v255, s5, 3
	v_lshlrev_b32_e32 v66, 3, v1
	s_cbranch_scc1 .LBB0_37
	s_mul_i32 s4, s8, 0x2100
	v_lshrrev_b32_e32 v75, 3, v1
	v_and_b32_e32 v0, 56, v66
	s_add_i32 s4, s4, 0
	v_lshrrev_b32_e32 v70, 5, v1
	v_and_b32_e32 v68, 31, v87
	v_mul_u32_u24_e32 v2, 0x84, v0
	v_lshlrev_b32_e32 v3, 2, v75
	v_or_b32_e32 v48, 24, v70
	v_add3_u32 v3, s4, v2, v3
	v_lshl_or_b32 v2, v70, 9, v68
	v_or_b32_e32 v60, 36, v70
	v_lshlrev_b32_e32 v5, 2, v2
	v_lshl_or_b32 v2, v48, 9, v68
	v_or_b32_e32 v72, 42, v70
	v_lshlrev_b32_e32 v29, 2, v2
	v_lshl_or_b32 v2, v60, 9, v68
	v_or_b32_e32 v74, 46, v70
	v_lshlrev_b32_e32 v41, 2, v2
	v_lshl_or_b32 v2, v72, 9, v68
	v_lshlrev_b32_e32 v47, 2, v2
	v_lshl_or_b32 v2, v74, 9, v68
	v_or_b32_e32 v76, 48, v70
	v_lshlrev_b32_e32 v51, 2, v2
	v_lshl_or_b32 v2, v76, 9, v68
	v_or_b32_e32 v77, 50, v70
	v_lshlrev_b32_e32 v53, 2, v2
	v_lshl_or_b32 v2, v77, 9, v68
	v_or_b32_e32 v78, 52, v70
	v_lshlrev_b32_e32 v55, 2, v2
	v_lshl_or_b32 v2, v78, 9, v68
	v_or_b32_e32 v79, 54, v70
	v_lshlrev_b32_e32 v57, 2, v2
	v_lshl_or_b32 v2, v79, 9, v68
	v_or_b32_e32 v80, 56, v70
	v_or_b32_e32 v26, 2, v70
	v_lshlrev_b32_e32 v59, 2, v2
	v_lshl_or_b32 v2, v80, 9, v68
	v_or_b32_e32 v81, 58, v70
	v_or_b32_e32 v50, 26, v70
	v_lshl_or_b32 v4, v26, 9, v68
	v_lshlrev_b32_e32 v61, 2, v2
	v_lshl_or_b32 v2, v81, 9, v68
	v_or_b32_e32 v82, 60, v70
	v_or_b32_e32 v62, 38, v70
	v_lshlrev_b32_e32 v7, 2, v4
	v_lshl_or_b32 v4, v50, 9, v68
	v_lshlrev_b32_e32 v63, 2, v2
	v_lshl_or_b32 v2, v82, 9, v68
	v_or_b32_e32 v83, 62, v70
	v_or_b32_e32 v73, 44, v70
	v_lshlrev_b32_e32 v31, 2, v4
	v_lshl_or_b32 v4, v62, 9, v68
	v_lshlrev_b32_e32 v67, 2, v2
	v_lshl_or_b32 v2, v83, 9, v68
	s_movk_i32 s5, 0x1c10
	v_lshlrev_b32_e32 v43, 2, v4
	v_lshl_or_b32 v4, v73, 9, v68
	v_lshlrev_b32_e32 v69, 2, v2
	v_mad_u32_u24 v2, v70, s5, v68
	v_lshlrev_b32_e32 v49, 2, v4
	v_add_u32_e32 v4, 0x3820, v2
	v_lshlrev_b32_e32 v89, 2, v4
	v_add_u32_e32 v4, 0x7040, v2
	v_lshlrev_b32_e32 v91, 2, v4
	v_add_u32_e32 v4, 0xa860, v2
	v_lshlrev_b32_e32 v93, 2, v4
	v_add_u32_e32 v4, 0xe080, v2
	v_lshlrev_b32_e32 v102, 2, v4
	v_add_u32_e32 v4, 0x118a0, v2
	v_lshlrev_b32_e32 v103, 2, v4
	v_add_u32_e32 v4, 0x150c0, v2
	v_lshlrev_b32_e32 v104, 2, v4
	v_add_u32_e32 v4, 0x188e0, v2
	v_lshlrev_b32_e32 v105, 2, v4
	v_add_u32_e32 v4, 0x1c100, v2
	v_lshlrev_b32_e32 v106, 2, v4
	v_add_u32_e32 v4, 0x1f920, v2
	v_lshlrev_b32_e32 v107, 2, v4
	v_add_u32_e32 v4, 0x23140, v2
	v_lshlrev_b32_e32 v108, 2, v4
	v_add_u32_e32 v4, 0x26960, v2
	v_lshlrev_b32_e32 v109, 2, v4
	v_add_u32_e32 v4, 0x2a180, v2
	v_lshlrev_b32_e32 v110, 2, v4
	v_add_u32_e32 v4, 0x2d9a0, v2
	v_lshlrev_b32_e32 v111, 2, v4
	v_add_u32_e32 v4, 0x311c0, v2
	v_lshlrev_b32_e32 v112, 2, v4
	v_add_u32_e32 v4, 0x349e0, v2
	v_lshlrev_b32_e32 v113, 2, v4
	v_add_u32_e32 v4, 0x38200, v2
	v_lshlrev_b32_e32 v114, 2, v4
	v_add_u32_e32 v4, 0x3ba20, v2
	v_lshlrev_b32_e32 v115, 2, v4
	v_add_u32_e32 v4, 0x3f240, v2
	v_lshlrev_b32_e32 v116, 2, v4
	v_add_u32_e32 v4, 0x42a60, v2
	v_lshlrev_b32_e32 v117, 2, v4
	v_add_u32_e32 v4, 0x46280, v2
	v_lshlrev_b32_e32 v118, 2, v4
	v_add_u32_e32 v4, 0x49aa0, v2
	v_lshlrev_b32_e32 v119, 2, v4
	v_add_u32_e32 v4, 0x4d2c0, v2
	v_lshlrev_b32_e32 v120, 2, v4
	v_add_u32_e32 v4, 0x50ae0, v2
	v_lshlrev_b32_e32 v121, 2, v4
	v_add_u32_e32 v4, 0x54300, v2
	v_lshlrev_b32_e32 v122, 2, v4
	v_add_u32_e32 v4, 0x57b20, v2
	v_lshlrev_b32_e32 v123, 2, v4
	v_add_u32_e32 v4, 0x5b340, v2
	v_lshlrev_b32_e32 v124, 2, v4
	v_add_u32_e32 v4, 0x5eb60, v2
	v_lshlrev_b32_e32 v125, 2, v4
	v_add_u32_e32 v4, 0x62380, v2
	v_lshlrev_b32_e32 v126, 2, v4
	v_add_u32_e32 v4, 0x65ba0, v2
	v_lshlrev_b32_e32 v127, 2, v4
	v_add_u32_e32 v4, 0x693c0, v2
	v_lshlrev_b32_e32 v129, 2, v2
; #define LAS __attribute__((address_space(3)))
; DI void transpose_item(const float* W, int ldw, bf16_t* WT, int ldt, LAS float* scr, int lane) {
;     float tv[32];
; #pragma unroll
;     for (int i = 0; i < 32; ++i) tv[i] = W[(size_t)(2 * i + (lane >> 5)) * ldw + (lane & 31)];
; #pragma unroll
;     for (int i = 0; i < 32; ++i) scr[(2 * i + (lane >> 5)) * 33 + (lane & 31)] = tv[i];
;     LDS_WAIT();
;     const int c = lane & 7;
; #pragma unroll
;     for (int j = 0; j < 4; ++j) {
;         const int n = (lane >> 3) + 8 * j; const LAS float* s = scr + (8 * c) * 33 + n;
;         u32x4 o; o.x = pk2(s[0 * 33], s[1 * 33]); o.y = pk2(s[2 * 33], s[3 * 33]); o.z = pk2(s[4 * 33], s[5 * 33]); o.w = pk2(s[6 * 33], s[7 * 33]);
;         *(u32x4*)(WT + (size_t)n * ldt + 8 * c) = o;
; DI void p0_prep(const Params& p, LAS unsigned char* lds) {
;     ...
;     constexpr int J1 = 28 * 128, J2 = J1 + 256, J3 = J2 + 256, J4 = J3 + 256, J5 = J4 + 128, J6 = J5 + 512;
;     for (int it = gw; it < J6; it += NGW) {
;         if (it < J1) {
;             int t = it >> 7; const int rem = it & 127, g = rem >> 4, kb = rem & 15; if (t >= 12) t += 1;
;             const bool sw = (t == 4 || t == 5 || t == 10 || t == 11);
;             const int src = (t < 12 ? 256 * t : 256 * (t - 1) + 16) + 32 * (sw ? g : lgrp(g));
;             transpose_item(p.w_in + (size_t)(64 * kb) * 7184 + src, 7184, (bf16_t*)(ws + OFF_WINT) + (size_t)(t * 256 + 32 * g) * 1024 + 64 * kb, 1024, scr, lane);
;         } else if (it < J2) {
;             const int j = it - J1, t = j >> 7, rem = j & 127, g = rem >> 4, kb = rem & 15;
;             const int src = 256 * t + 32 * (t ? g : lgrp(g));
;             transpose_item(p.w_mem_kv + (size_t)(64 * kb) * 512 + src, 512, (bf16_t*)(ws + OFF_WMEM) + (size_t)(t * 256 + 32 * g) * 1024 + 64 * kb, 1024, scr, lane);
;         } else if (it < J4) {
;             const int j0 = it - J2, which = j0 >> 8, j = j0 & 255, t = j >> 6, rem = j & 63, g = rem >> 3, kb = rem & 7;
;             const float* W = which ? p.w_up_b : p.w_up_a;
;             transpose_item(W + (size_t)(64 * kb) * 1024 + 256 * t + 32 * lgrp(g), 1024, (bf16_t*)(ws + (which ? OFF_WUPB : OFF_WUPA)) + (size_t)(t * 256 + 32 * g) * 512 + 64 * kb, 512, scr, lane);
;         } else if (it < J5) {
;             const int j = it - J4, t = j >> 5, rem = j & 31, g = rem >> 2, kb = rem & 3;
	v_add_u32_e32 v2, 0x6cbe0, v2
	v_lshlrev_b32_e32 v130, 2, v2
	s_movk_i32 s5, 0x84
	v_mov_b32_e32 v2, 0x630
	v_mad_u32_u24 v131, v70, s5, v2
	v_mov_b32_e32 v2, 0xc60
	v_mad_u32_u24 v132, v70, s5, v2
	v_mov_b32_e32 v2, 0x1290
	v_mad_u32_u24 v133, v70, s5, v2
	v_mov_b32_e32 v2, 0x18c0
	v_or_b32_e32 v28, 4, v70
	v_mad_u32_u24 v134, v70, s5, v2
	v_lshl_add_u32 v135, v68, 2, s4
	s_load_dwordx4 s[4:7], s[0:1], 0xb0
	s_load_dwordx2 s[10:11], s[0:1], 0x88
	s_load_dwordx2 s[12:13], s[0:1], 0x48
	v_or_b32_e32 v30, 6, v70
	v_or_b32_e32 v32, 8, v70
	v_or_b32_e32 v34, 10, v70
	v_or_b32_e32 v38, 14, v70
	v_or_b32_e32 v42, 18, v70
	v_or_b32_e32 v52, 28, v70
	v_lshl_or_b32 v6, v28, 9, v68
	v_or_b32_e32 v36, 12, v70
	v_or_b32_e32 v40, 16, v70
	v_or_b32_e32 v44, 20, v70
	v_or_b32_e32 v46, 22, v70
	v_or_b32_e32 v54, 30, v70
	v_or_b32_e32 v56, 32, v70
	v_or_b32_e32 v58, 34, v70
	v_or_b32_e32 v71, 40, v70
	v_lshl_or_b32 v8, v30, 9, v68
	v_lshl_or_b32 v10, v32, 9, v68
	v_lshl_or_b32 v12, v34, 9, v68
	v_lshl_or_b32 v16, v38, 9, v68
	v_lshl_or_b32 v20, v42, 9, v68
	v_lshlrev_b32_e32 v9, 2, v6
	v_lshl_or_b32 v6, v52, 9, v68
	v_lshl_or_b32 v14, v36, 9, v68
	v_lshl_or_b32 v18, v40, 9, v68
	v_lshl_or_b32 v22, v44, 9, v68
	v_lshl_or_b32 v24, v46, 9, v68
	v_lshlrev_b32_e32 v11, 2, v8
	v_lshlrev_b32_e32 v13, 2, v10
	v_lshlrev_b32_e32 v15, 2, v12
	v_lshl_or_b32 v8, v54, 9, v68
	v_lshlrev_b32_e32 v19, 2, v16
	v_lshl_or_b32 v10, v56, 9, v68
	v_lshlrev_b32_e32 v23, 2, v20
	v_lshl_or_b32 v12, v58, 9, v68
	v_lshlrev_b32_e32 v33, 2, v6
	v_lshl_or_b32 v6, v71, 9, v68
	v_lshl_or_b32 v2, v26, 10, v68
	v_lshl_or_b32 v16, v40, 10, v68
	v_lshl_or_b32 v20, v44, 10, v68
	v_lshl_or_b32 v26, v50, 10, v68
	v_lshl_or_b32 v40, v71, 10, v68
	v_lshl_or_b32 v44, v73, 10, v68
	v_lshl_or_b32 v50, v77, 10, v68
	v_or_b32_e32 v71, 8, v75
	v_or_b32_e32 v73, 16, v75
	v_or_b32_e32 v77, 24, v75
	v_lshlrev_b32_e32 v17, 2, v14
	v_lshlrev_b32_e32 v21, 2, v18
	v_lshlrev_b32_e32 v25, 2, v22
	v_lshlrev_b32_e32 v27, 2, v24
	v_lshlrev_b32_e32 v35, 2, v8
	v_lshlrev_b32_e32 v37, 2, v10
	v_lshlrev_b32_e32 v39, 2, v12
	v_lshlrev_b32_e32 v45, 2, v6
	v_lshlrev_b32_e32 v128, 2, v4
	s_mov_b64 s[14:15], 0x1100000
	v_lshl_or_b32 v4, v28, 10, v68
	v_lshl_or_b32 v6, v30, 10, v68
	v_lshl_or_b32 v8, v32, 10, v68
	v_lshl_or_b32 v10, v34, 10, v68
	v_lshl_or_b32 v12, v36, 10, v68
	v_lshl_or_b32 v14, v38, 10, v68
	v_lshl_or_b32 v18, v42, 10, v68
	v_lshl_or_b32 v22, v46, 10, v68
	v_lshl_or_b32 v24, v48, 10, v68
	v_lshl_or_b32 v28, v52, 10, v68
	v_lshl_or_b32 v30, v54, 10, v68
	v_lshl_or_b32 v32, v56, 10, v68
	v_lshl_or_b32 v34, v58, 10, v68
	v_lshl_or_b32 v36, v60, 10, v68
	v_lshl_or_b32 v38, v62, 10, v68
	v_lshl_or_b32 v42, v72, 10, v68
	v_lshl_or_b32 v46, v74, 10, v68
	v_lshl_or_b32 v48, v76, 10, v68
	v_lshl_or_b32 v52, v78, 10, v68
	v_lshl_or_b32 v54, v79, 10, v68
	v_lshl_or_b32 v56, v80, 10, v68
	v_lshl_or_b32 v58, v81, 10, v68
	v_lshl_or_b32 v60, v82, 10, v68
	v_lshl_or_b32 v62, v83, 10, v68
	v_lshl_or_b32 v68, v70, 10, v68
	v_mul_u32_u24_e32 v136, 0x84, v70
	s_mov_b64 s[28:29], 0x1080000
	s_mov_b64 s[30:31], 0x1300000
	s_lshl_b32 s16, s2, 4
	s_lshl_b32 s17, s8, 1
	s_lshl_b32 s18, s2, 6
	s_lshl_b32 s19, s8, 3
	s_lshl_b32 s21, s2, 9
	s_lshl_b32 s22, s8, 6
	s_lshl_b32 s23, s2, 5
	s_lshl_b32 s8, s8, 2
	v_lshlrev_b32_e32 v70, 8, v75
	v_lshlrev_b32_e32 v72, 8, v71
	v_lshlrev_b32_e32 v74, 8, v73
	v_lshlrev_b32_e32 v76, 8, v77
	v_lshlrev_b32_e32 v78, 9, v75
	v_lshlrev_b32_e32 v80, 9, v71
	v_lshlrev_b32_e32 v82, 9, v73
	v_lshlrev_b32_e32 v84, 9, v77
	s_mov_b32 s9, 0
	s_add_i32 s16, s16, s17
	s_lshl_b32 s17, s3, 4
	s_add_i32 s18, s18, s19
	s_lshl_b32 s19, s3, 6
	s_add_i32 s21, s21, s22
	s_lshl_b32 s22, s3, 9
	s_add_i32 s23, s23, s8
	s_lshl_b32 s24, s3, 5
	v_lshlrev_b32_e32 v70, 1, v70
	v_lshlrev_b32_e32 v72, 1, v72
	v_lshlrev_b32_e32 v74, 1, v74
	v_lshlrev_b32_e32 v76, 1, v76
	s_mov_b32 s25, 0xe80000
	s_movk_i32 s26, 0xa0
	v_lshlrev_b32_e32 v78, 1, v78
	v_lshlrev_b32_e32 v80, 1, v80
	v_lshlrev_b32_e32 v82, 1, v82
	v_lshlrev_b32_e32 v84, 1, v84
	s_mov_b32 s27, s20
	v_lshlrev_b32_e32 v86, 10, v75
	v_lshlrev_b32_e32 v88, 10, v71
	v_lshlrev_b32_e32 v90, 10, v73
	v_lshlrev_b32_e32 v92, 10, v77
	v_lshl_add_u64 v[94:95], v[64:65], 0, s[14:15]
	v_mov_b32_e32 v97, 0
	v_lshl_add_u64 v[98:99], v[64:65], 0, s[28:29]
	v_lshl_add_u64 v[100:101], v[64:65], 0, s[30:31]
	s_branch .LBB0_21

; DI void p2_mixers(const Params& p, LAS unsigned char* lds) {
;     ...
;     for (int it = gw, stage2 = 0;; it += NGW) {
;         if (!stage2 && it >= 4096) { stage2 = 1; it = 4096 + gw; }
;         if (stage2 && it >= 4352) break;
;         AttnItem a;
;         a.qld = 512; a.kld = 512; a.zold = 512;
;         if (it < 4096) {
;             const int head = it & 7, half = (it >> 3) & 1, c = (it >> 4) & 127, b = it >> 11;
;             const int cs = c > 8 ? c - 8 : 0, kstart = 64 * cs, tq = b * 8192 + 64 * c + 32 * half;
;             a.q = (const bf16_t*)(ws + OFF_QA) + (size_t)tq * 512 + head * 64; a.nq = 32;
;             a.k = (const bf16_t*)(ws + OFF_KA) + (size_t)(b * 8192 + kstart) * 512 + head * 64;
;             a.vt = (const bf16_t*)(ws + OFF_VAT) + (size_t)(b * 512 + head * 64) * VLD + kstart; a.vtld = VLD;
;             a.nkeys = 64 * (c - cs + 1); a.nkb = a.nkeys >> 5;
;             a.bias = tab + head * 257; a.qpos0 = 64 * c + 32 * half - kstart;
;             a.zo = (bf16_t*)(ws + OFF_ZA) + (size_t)tq * 512 + head * 64;
.LBB0_937:
	s_cmpk_gt_i32 s61, 0xfff
	s_cbranch_scc1 .Lat_single
	s_cmpk_gt_i32 s61, 0x7ff
	s_cbranch_scc1 .Lat_ret_band
	s_and_b32 s12, s61, 7
	s_bfe_u32 s14, s61, 0x70003
	s_lshr_b32 s15, s61, 10
	s_sub_u32 s16, s14, 8
	s_max_i32 s16, s16, 0
	s_lshl_b32 s17, s16, 6
	s_lshl_b32 s18, s15, 13
	s_lshl_b32 s19, s14, 6
	s_add_i32 s19, s19, s18
	s_lshl_b32 s21, s12, 7
	s_lshl_b32 s32, s19, 10
	s_add_i32 s32, s32, s21
	s_add_u32 s50, s44, 0x3600000
	s_addc_u32 s51, s45, 0
	s_add_u32 s50, s50, s32
	s_addc_u32 s51, s51, 0
	s_add_u32 s56, s44, 0x87d0000
	s_addc_u32 s57, s45, 0
	s_add_u32 s56, s56, s32
	s_addc_u32 s57, s57, 0
	s_add_i32 s32, s18, s17
	s_lshl_b32 s32, s32, 10
	s_add_i32 s32, s32, s21
	s_add_u32 s52, s44, 0x4680000
	s_addc_u32 s53, s45, 0
	s_add_u32 s52, s52, s32
	s_addc_u32 s53, s53, 0
	s_lshl_b32 s32, s15, 3
	s_add_i32 s32, s32, s12
	s_lshl_b32 s32, s32, 8
	s_lshr_b32 s39, s17, 5
	s_add_i32 s32, s32, s39
	s_lshl_b32 s32, s32, 12
	s_add_u32 s54, s44, 0x5680000
	s_addc_u32 s55, s45, 0
	s_add_u32 s54, s54, s32
	s_addc_u32 s55, s55, 0
	s_sub_i32 s32, s14, s16
	s_lshl_b32 s66, s32, 6
	s_add_i32 s32, s32, 1
	s_lshl_b32 s65, s32, 1
	s_mul_i32 s67, s12, 0x404
	s_branch .Lat2_entry

; #define LAS __attribute__((address_space(3)))
; #define ATT_LOAD(KR, VR, kb_) do { _Pragma("unroll") for (int i = 0; i < 4; ++i) { KR[i] = *(const u32x4*)(kg + (size_t)(32 * (kb_) + 8 * i) * it.kld); VR[i] = *(const u32x4*)(vg + (size_t)(16 * i) * it.vtld + 32 * (kb_)); } } while (0)
; DI void attn_item(const AttnItem& it, LAS unsigned char* wl, int lane) {
;     const int qi = lane & 31, hh = lane >> 5;
;     const int qr = qi < it.nq ? qi : it.nq - 1;
;     bf16x8 bq[4];
; #pragma unroll
;     for (int kk = 0; kk < 4; ++kk) bq[kk] = *(const bf16x8*)(it.q + (size_t)qr * it.qld + 16 * kk + 8 * hh);
;     float mrun = -1e30f, lsum = 0.f;
;     f32x16 o0, o1;
; #pragma unroll
;     for (int r = 0; r < 16; ++r) { o0[r] = 0.f; o1[r] = 0.f; }
;     const int krow = lane >> 3, kch = lane & 7, vrow = lane >> 2, vch = lane & 3;
;     const bf16_t* kg = it.k + (size_t)krow * it.kld + 8 * kch;
;     const bf16_t* vg = it.vt + (size_t)vrow * it.vtld + 8 * vch;
;     LAS unsigned char* Kl = wl; LAS unsigned char* Vl = wl + 4608;
;     const unsigned kw = krow * 144 + kch * 16, vw = vrow * 80 + vch * 16;
;     const unsigned kr = qi * 144 + hh * 16, vr = qi * 80 + hh * 8;
;     u32x4 kA[4], vA[4], kB[4], vB[4];
;     ...
;     ATT_LOAD(kA, vA, 0);
;     if (it.nkb > 1) ATT_LOAD(kB, vB, 1);
.Lat_band_done_2:
	s_movk_i32 s58, 0x400
	s_mul_i32 s67, s12, 0x404
	s_mov_b32 s68, 1
	s_mov_b32 s69, 0
.Lat_entry:
	v_and_b32_e32 v108, 31, v203
	v_bfe_u32 v109, v203, 5, 1
	v_and_b32_e32 v110, 63, v203
	s_add_i32 s70, s49, 0x2100
	s_add_i32 s77, s63, -1
	v_min_u32_e32 v97, s77, v108
	v_mul_lo_u32 v97, v97, s58
	v_lshl_add_u32 v97, v109, 4, v97
	global_load_dwordx4 v[0:3], v97, s[50:51]
	global_load_dwordx4 v[4:7], v97, s[50:51] offset:32
	global_load_dwordx4 v[8:11], v97, s[50:51] offset:64
	global_load_dwordx4 v[12:15], v97, s[50:51] offset:96
	v_lshrrev_b32_e32 v96, 4, v110
	v_and_b32_e32 v104, 7, v110
	v_lshrrev_b32_e32 v100, 3, v110
	v_xor_b32_e32 v101, v104, v96
	v_add_u32_e32 v102, 0, v100
	v_mul_lo_u32 v102, v102, s58
	v_lshl_add_u32 v228, v101, 4, v102
	v_xor_b32_e32 v101, v104, v96
	v_xor_b32_e32 v101, 4, v101
	v_add_u32_e32 v102, 8, v100
	v_mul_lo_u32 v102, v102, s58
	v_lshl_add_u32 v229, v101, 4, v102
	v_xor_b32_e32 v101, v104, v96
	v_add_u32_e32 v102, 16, v100
	v_mul_lo_u32 v102, v102, s58
	v_lshl_add_u32 v230, v101, 4, v102
	v_xor_b32_e32 v101, v104, v96
	v_xor_b32_e32 v101, 4, v101
	v_add_u32_e32 v102, 24, v100
	v_mul_lo_u32 v102, v102, s58
	v_lshl_add_u32 v231, v101, 4, v102
	v_and_b32_e32 v104, 3, v110
	v_xor_b32_e32 v101, v104, v96
	v_lshrrev_b32_e32 v100, 2, v110
	v_add_u32_e32 v102, 0, v100
	v_mul_lo_u32 v102, v102, s59
	v_lshl_add_u32 v232, v101, 4, v102
	v_add_u32_e32 v102, 16, v100
	v_mul_lo_u32 v102, v102, s59
	v_lshl_add_u32 v233, v101, 4, v102
	v_add_u32_e32 v102, 32, v100
	v_mul_lo_u32 v102, v102, s59
	v_lshl_add_u32 v234, v101, 4, v102
	v_add_u32_e32 v102, 48, v100
	v_mul_lo_u32 v102, v102, s59
	v_lshl_add_u32 v235, v101, 4, v102
	v_bfe_u32 v96, v108, 1, 3
	v_lshl_add_u32 v102, v108, 7, s70
	v_or_b32_e32 v101, 0, v109
	v_xor_b32_e32 v101, v101, v96
	v_lshl_add_u32 v236, v101, 4, v102
	v_or_b32_e32 v101, 2, v109
	v_xor_b32_e32 v101, v101, v96
	v_lshl_add_u32 v237, v101, 4, v102
	v_or_b32_e32 v101, 4, v109
	v_xor_b32_e32 v101, v101, v96
	v_lshl_add_u32 v238, v101, 4, v102
	v_or_b32_e32 v101, 6, v109
	v_xor_b32_e32 v101, v101, v96
	v_lshl_add_u32 v239, v101, 4, v102
	v_bfe_u32 v96, v108, 2, 2
	v_lshl_add_u32 v102, v108, 6, s70
	v_lshl_add_u32 v102, v109, 3, v102
	v_add_u32_e32 v102, 0x1000, v102
	v_xor_b32_e32 v101, 0, v96
	v_lshl_add_u32 v240, v101, 4, v102
	v_xor_b32_e32 v101, 1, v96
	v_lshl_add_u32 v241, v101, 4, v102
	v_xor_b32_e32 v101, 2, v96
	v_lshl_add_u32 v242, v101, 4, v102
	v_xor_b32_e32 v101, 3, v96
	v_lshl_add_u32 v243, v101, 4, v102
	v_lshlrev_b32_e32 v101, 2, v109
	v_sub_u32_e32 v101, v108, v101
	v_add_u32_e32 v101, 0x80, v101
	v_lshlrev_b32_e32 v244, 2, v101
	v_mul_lo_u32 v245, v108, s58
	v_lshl_add_u32 v245, v109, 3, v245
	s_lshl_b32 s75, s58, 5
	s_add_i32 s76, s67, 0x400
	s_mov_b32 s78, 0
	s_cmp_eq_u32 s68, 0
	s_cbranch_scc1 .Lat_nob_3
	v_mov_b32_e32 v110, s76
	ds_read_b32 v110, v110
	s_waitcnt lgkmcnt(0)
	s_nop 0
	v_readfirstlane_b32 s78, v110

; #define LAS __attribute__((address_space(3)))
; #define ATT_LOAD(KR, VR, kb_) do { _Pragma("unroll") for (int i = 0; i < 4; ++i) { KR[i] = *(const u32x4*)(kg + (size_t)(32 * (kb_) + 8 * i) * it.kld); VR[i] = *(const u32x4*)(vg + (size_t)(16 * i) * it.vtld + 32 * (kb_)); } } while (0)
; DI void attn_item(const AttnItem& it, LAS unsigned char* wl, int lane) {
;     const int qi = lane & 31, hh = lane >> 5;
;     const int qr = qi < it.nq ? qi : it.nq - 1;
;     bf16x8 bq[4];
; #pragma unroll
;     for (int kk = 0; kk < 4; ++kk) bq[kk] = *(const bf16x8*)(it.q + (size_t)qr * it.qld + 16 * kk + 8 * hh);
;     float mrun = -1e30f, lsum = 0.f;
;     f32x16 o0, o1;
; #pragma unroll
;     for (int r = 0; r < 16; ++r) { o0[r] = 0.f; o1[r] = 0.f; }
;     const int krow = lane >> 3, kch = lane & 7, vrow = lane >> 2, vch = lane & 3;
;     const bf16_t* kg = it.k + (size_t)krow * it.kld + 8 * kch;
;     const bf16_t* vg = it.vt + (size_t)vrow * it.vtld + 8 * vch;
;     LAS unsigned char* Kl = wl; LAS unsigned char* Vl = wl + 4608;
;     const unsigned kw = krow * 144 + kch * 16, vw = vrow * 80 + vch * 16;
;     const unsigned kr = qi * 144 + hh * 16, vr = qi * 80 + hh * 8;
;     u32x4 kA[4], vA[4], kB[4], vB[4];
;     ...
;     ATT_LOAD(kA, vA, 0);
;     if (it.nkb > 1) ATT_LOAD(kB, vB, 1);
.Lat2_entry:
	v_and_b32_e32 v110, 31, v203
	v_bfe_u32 v166, v203, 5, 1
	v_and_b32_e32 v108, 63, v203
	s_add_i32 s70, s49, 0x2100
	v_lshlrev_b32_e32 v197, 10, v110
	v_lshl_add_u32 v197, v166, 4, v197
	global_load_dwordx4 v[0:3], v197, s[50:51]
	global_load_dwordx4 v[4:7], v197, s[50:51] offset:32
	global_load_dwordx4 v[8:11], v197, s[50:51] offset:64
	global_load_dwordx4 v[12:15], v197, s[50:51] offset:96
	v_add_u32_e32 v197, 0x8000, v197
	global_load_dwordx4 v[16:19], v197, s[50:51]
	global_load_dwordx4 v[20:23], v197, s[50:51] offset:32
	global_load_dwordx4 v[24:27], v197, s[50:51] offset:64
	global_load_dwordx4 v[28:31], v197, s[50:51] offset:96
	v_lshrrev_b32_e32 v196, 4, v108
	v_and_b32_e32 v109, 7, v108
	v_lshrrev_b32_e32 v198, 3, v108
	v_xor_b32_e32 v199, v109, v196
	v_add_u32_e32 v200, 0, v198
	v_lshlrev_b32_e32 v200, 10, v200
	v_lshl_add_u32 v244, v199, 4, v200
	v_xor_b32_e32 v199, v109, v196
	v_xor_b32_e32 v199, 4, v199
	v_add_u32_e32 v200, 8, v198
	v_lshlrev_b32_e32 v200, 10, v200
	v_lshl_add_u32 v245, v199, 4, v200
	v_xor_b32_e32 v199, v109, v196
	v_add_u32_e32 v200, 16, v198
	v_lshlrev_b32_e32 v200, 10, v200
	v_lshl_add_u32 v246, v199, 4, v200
	v_xor_b32_e32 v199, v109, v196
	v_xor_b32_e32 v199, 4, v199
	v_add_u32_e32 v200, 24, v198
	v_lshlrev_b32_e32 v200, 10, v200
	v_lshl_add_u32 v247, v199, 4, v200
	v_and_b32_e32 v109, 3, v108
	v_xor_b32_e32 v199, v109, v196
	v_lshrrev_b32_e32 v198, 2, v108
	v_add_u32_e32 v200, 0, v198
	v_lshlrev_b32_e32 v200, 6, v200
	v_lshl_add_u32 v248, v199, 4, v200
	v_add_u32_e32 v200, 16, v198
	v_lshlrev_b32_e32 v200, 6, v200
	v_lshl_add_u32 v249, v199, 4, v200
	v_add_u32_e32 v200, 32, v198
	v_lshlrev_b32_e32 v200, 6, v200
	v_lshl_add_u32 v250, v199, 4, v200
	v_add_u32_e32 v200, 48, v198
	v_lshlrev_b32_e32 v200, 6, v200
	v_lshl_add_u32 v251, v199, 4, v200
	v_bfe_u32 v196, v110, 1, 3
	v_lshl_add_u32 v200, v110, 7, s70
	v_or_b32_e32 v199, 0, v166
	v_xor_b32_e32 v199, v199, v196
	v_lshl_add_u32 v252, v199, 4, v200
	v_or_b32_e32 v199, 2, v166
	v_xor_b32_e32 v199, v199, v196
	v_lshl_add_u32 v253, v199, 4, v200
	v_or_b32_e32 v199, 4, v166
	v_xor_b32_e32 v199, v199, v196
	v_lshl_add_u32 v254, v199, 4, v200
	v_or_b32_e32 v199, 6, v166
	v_xor_b32_e32 v199, v199, v196
	v_lshl_add_u32 v204, v199, 4, v200
	v_bfe_u32 v196, v110, 2, 2
	v_lshl_add_u32 v200, v110, 6, s70
	v_lshl_add_u32 v200, v166, 3, v200
	v_add_u32_e32 v200, 0x1000, v200
	v_xor_b32_e32 v199, 0, v196
	v_lshl_add_u32 v205, v199, 4, v200
	v_xor_b32_e32 v199, 1, v196
	v_lshl_add_u32 v206, v199, 4, v200
	v_xor_b32_e32 v199, 2, v196
	v_lshl_add_u32 v207, v199, 4, v200
	v_xor_b32_e32 v199, 3, v196
	v_lshl_add_u32 v208, v199, 4, v200
	v_lshlrev_b32_e32 v199, 2, v166
	v_sub_u32_e32 v199, v110, v199
	v_add_u32_e32 v199, 0x80, v199
	v_lshlrev_b32_e32 v167, 2, v199
	v_lshlrev_b32_e32 v168, 10, v110
	v_lshl_add_u32 v168, v166, 3, v168
	s_mov_b32 s75, 0x8000
	s_add_i32 s76, s67, 0x400
	v_mov_b32_e32 v108, s76
	ds_read_b32 v108, v108
	s_waitcnt lgkmcnt(0)
	s_nop 0
	v_readfirstlane_b32 s78, v108
	v_mov_b32_e32 v150, 0xf149f2ca
	v_mov_b32_e32 v152, 0
	v_mov_b32_e32 v32, 0
	v_mov_b32_e32 v48, 0
	v_mov_b32_e32 v33, 0
	v_mov_b32_e32 v49, 0
	v_mov_b32_e32 v34, 0
	v_mov_b32_e32 v50, 0
	v_mov_b32_e32 v35, 0
	v_mov_b32_e32 v51, 0
	v_mov_b32_e32 v36, 0
	v_mov_b32_e32 v52, 0
	v_mov_b32_e32 v37, 0
	v_mov_b32_e32 v53, 0
	v_mov_b32_e32 v38, 0
	v_mov_b32_e32 v54, 0
	v_mov_b32_e32 v39, 0
	v_mov_b32_e32 v55, 0
	v_mov_b32_e32 v40, 0
	v_mov_b32_e32 v56, 0
	v_mov_b32_e32 v41, 0
	v_mov_b32_e32 v57, 0
	v_mov_b32_e32 v42, 0
	v_mov_b32_e32 v58, 0
	v_mov_b32_e32 v43, 0
	v_mov_b32_e32 v59, 0
	v_mov_b32_e32 v44, 0
	v_mov_b32_e32 v60, 0
	v_mov_b32_e32 v45, 0
	v_mov_b32_e32 v61, 0
	v_mov_b32_e32 v46, 0
	v_mov_b32_e32 v62, 0
	v_mov_b32_e32 v47, 0
	v_mov_b32_e32 v63, 0
	v_mov_b32_e32 v151, 0xf149f2ca
	v_mov_b32_e32 v157, 0
	v_mov_b32_e32 v64, 0
	v_mov_b32_e32 v80, 0
	v_mov_b32_e32 v65, 0
	v_mov_b32_e32 v81, 0
	v_mov_b32_e32 v66, 0
	v_mov_b32_e32 v82, 0
	v_mov_b32_e32 v67, 0
	v_mov_b32_e32 v83, 0
	v_mov_b32_e32 v68, 0
	v_mov_b32_e32 v84, 0
	v_mov_b32_e32 v69, 0
	v_mov_b32_e32 v85, 0
	v_mov_b32_e32 v70, 0
	v_mov_b32_e32 v86, 0
	v_mov_b32_e32 v71, 0
	v_mov_b32_e32 v87, 0
	v_mov_b32_e32 v72, 0
	v_mov_b32_e32 v88, 0
	v_mov_b32_e32 v73, 0
	v_mov_b32_e32 v89, 0
	v_mov_b32_e32 v74, 0
	v_mov_b32_e32 v90, 0
	v_mov_b32_e32 v75, 0
	v_mov_b32_e32 v91, 0
	v_mov_b32_e32 v76, 0
	v_mov_b32_e32 v92, 0
	v_mov_b32_e32 v77, 0
	v_mov_b32_e32 v93, 0
	v_mov_b32_e32 v78, 0
	v_mov_b32_e32 v94, 0
	v_mov_b32_e32 v79, 0
	v_mov_b32_e32 v95, 0
	s_mov_b32 s71, 0
	s_add_i32 m0, s70, 0x0
	s_nop 0
	global_load_lds_dwordx4 v244, s[52:53]
	s_add_i32 m0, s70, 0x400
	s_nop 0
	global_load_lds_dwordx4 v245, s[52:53]
	s_add_i32 m0, s70, 0x800
	s_nop 0
	global_load_lds_dwordx4 v246, s[52:53]
	s_add_i32 m0, s70, 0xc00
	s_nop 0
	global_load_lds_dwordx4 v247, s[52:53]
	s_add_u32 s52, s52, s75
	s_addc_u32 s53, s53, 0
	s_add_i32 m0, s70, 0x1000
	s_nop 0
	global_load_lds_dwordx4 v248, s[54:55]
	s_add_i32 m0, s70, 0x1400
	s_nop 0
	global_load_lds_dwordx4 v249, s[54:55]
	s_add_i32 m0, s70, 0x1800
	s_nop 0
	global_load_lds_dwordx4 v250, s[54:55]
	s_add_i32 m0, s70, 0x1c00
	s_nop 0
	global_load_lds_dwordx4 v251, s[54:55]
	s_add_u32 s54, s54, 0x1000
	s_addc_u32 s55, s55, 0
	s_add_i32 m0, s70, 0x2000
	s_nop 0
	global_load_lds_dwordx4 v244, s[52:53]
	s_add_i32 m0, s70, 0x2400
	s_nop 0
	global_load_lds_dwordx4 v245, s[52:53]
	s_add_i32 m0, s70, 0x2800
	s_nop 0
	global_load_lds_dwordx4 v246, s[52:53]
	s_add_i32 m0, s70, 0x2c00
	s_nop 0
	global_load_lds_dwordx4 v247, s[52:53]
	s_add_u32 s52, s52, s75
	s_addc_u32 s53, s53, 0
	s_add_i32 m0, s70, 0x3000
	s_nop 0
	global_load_lds_dwordx4 v248, s[54:55]
	s_add_i32 m0, s70, 0x3400
	s_nop 0
	global_load_lds_dwordx4 v249, s[54:55]
	s_add_i32 m0, s70, 0x3800
	s_nop 0
	global_load_lds_dwordx4 v250, s[54:55]
	s_add_i32 m0, s70, 0x3c00
	s_nop 0
	global_load_lds_dwordx4 v251, s[54:55]
	s_add_u32 s54, s54, 0x1000
	s_addc_u32 s55, s55, 0
; #define LAS __attribute__((address_space(3)))
; #define MFMA32(a, b, c) __builtin_amdgcn_mfma_f32_32x32x16_bf16((a), (b), (c), 0, 0, 0)
; #define ATT_LOAD(KR, VR, kb_) do { _Pragma("unroll") for (int i = 0; i < 4; ++i) { KR[i] = *(const u32x4*)(kg + (size_t)(32 * (kb_) + 8 * i) * it.kld); VR[i] = *(const u32x4*)(vg + (size_t)(16 * i) * it.vtld + 32 * (kb_)); } } while (0)
; #define ATT_STORE(KR, VR) do { _Pragma("unroll") for (int i = 0; i < 4; ++i) { *(LAS u32x4*)(Kl + kw + i * 1152) = KR[i]; *(LAS u32x4*)(Vl + vw + i * 1280) = VR[i]; } } while (0)
; DI void attn_block(const AttnItem& it, int key0, int qi, int hh, const bf16x8 (&bq)[4], LAS unsigned char* Kl, LAS unsigned char* Vl, unsigned kr, unsigned vr,
;                    float& mrun, float& lsum, f32x16& o0, f32x16& o1) {
;     f32x16 s;
; #pragma unroll
;     for (int r = 0; r < 16; ++r) s[r] = 0.f;
; #pragma unroll
;     for (int kk = 0; kk < 4; ++kk) { const bf16x8 ak = *(const LAS bf16x8*)(Kl + kr + kk * 32); s = MFMA32(ak, bq[kk], s); }
;     if (it.bias) {
;         const int d0 = it.qpos0 - key0;
;         if (d0 - 31 >= 128) {
;             const float bc = it.bias[256];
; #pragma unroll
;             for (int r = 0; r < 16; ++r) s[r] += bc;
;         } else {
; #pragma unroll
;             for (int r = 0; r < 16; ++r) {
;                 int d = d0 + qi - ((r & 3) + 8 * (r >> 2) + 4 * hh);
;                 d = d < -128 ? -128 : (d > 128 ? 128 : d);
;                 s[r] += it.bias[d + 128];
;             }
;         }
;     }
; DI void attn_item(const AttnItem& it, LAS unsigned char* wl, int lane) {
;     ...
;     for (int kb = 0; kb < it.nkb; kb += 2) {
;         ATT_STORE(kA, vA);
;         if (kb + 2 < it.nkb) ATT_LOAD(kA, vA, kb + 2);
.Lat2_loop:
	s_add_i32 s79, s71, 1
	s_add_i32 s77, s71, 2
	s_cmp_lt_u32 s79, s65
	s_cbranch_scc1 .Lat_k12_2001
	s_waitcnt vmcnt(4)
	s_branch .Lat_kdone_2002
.Lat_k12_2001:
	s_waitcnt vmcnt(12)
.Lat_kdone_2002:
	ds_read_b128 v[96:99], v252 offset:0
	ds_read_b128 v[100:103], v253 offset:0
	ds_read_b128 v[104:107], v254 offset:0
	ds_read_b128 v[116:119], v204 offset:0
	s_waitcnt lgkmcnt(0)
	v_mfma_f32_32x32x16_bf16 v[212:227], v[96:99], v[0:3], 0
	v_mfma_f32_32x32x16_bf16 v[212:227], v[100:103], v[4:7], v[212:227]
	v_mfma_f32_32x32x16_bf16 v[212:227], v[104:107], v[8:11], v[212:227]
	v_mfma_f32_32x32x16_bf16 v[212:227], v[116:119], v[12:15], v[212:227]
	v_mfma_f32_32x32x16_bf16 v[228:243], v[96:99], v[16:19], 0
	v_mfma_f32_32x32x16_bf16 v[228:243], v[100:103], v[20:23], v[228:243]
	v_mfma_f32_32x32x16_bf16 v[228:243], v[104:107], v[24:27], v[228:243]
	v_mfma_f32_32x32x16_bf16 v[228:243], v[116:119], v[28:31], v[228:243]
	s_nop 3
	s_cmp_lt_u32 s77, s65
	s_cbranch_scc0 .Lat_nokd_2003
	s_add_i32 m0, s70, 0x0
	s_nop 0
	global_load_lds_dwordx4 v244, s[52:53]
	s_add_i32 m0, s70, 0x400
	s_nop 0
	global_load_lds_dwordx4 v245, s[52:53]
	s_add_i32 m0, s70, 0x800
	s_nop 0
	global_load_lds_dwordx4 v246, s[52:53]
	s_add_i32 m0, s70, 0xc00
	s_nop 0
	global_load_lds_dwordx4 v247, s[52:53]
	s_add_u32 s52, s52, s75
	s_addc_u32 s53, s53, 0
.Lat_nokd_2003:
	s_add_i32 s85, s66, 0
	s_cmpk_ge_i32 s85, 0x9f
	s_cbranch_scc1 .Lat_far_2008
	s_lshl_b32 s82, s85, 2
	s_add_i32 s82, s82, s67
	v_add_u32_e32 v202, s82, v167
	v_min_u32_e32 v174, s76, v202
	v_subrev_u32_e32 v175, 4, v202
	v_min_u32_e32 v175, s76, v175
	v_subrev_u32_e32 v176, 8, v202
	v_min_u32_e32 v176, s76, v176
	v_subrev_u32_e32 v177, 12, v202
	v_min_u32_e32 v177, s76, v177
	v_subrev_u32_e32 v178, 32, v202
	v_min_u32_e32 v178, s76, v178
	v_subrev_u32_e32 v179, 36, v202
	v_min_u32_e32 v179, s76, v179
	v_subrev_u32_e32 v180, 40, v202
	v_min_u32_e32 v180, s76, v180
	v_subrev_u32_e32 v181, 44, v202
	v_min_u32_e32 v181, s76, v181
	v_subrev_u32_e32 v182, 64, v202
	v_min_u32_e32 v182, s76, v182
	v_subrev_u32_e32 v183, 68, v202
	v_min_u32_e32 v183, s76, v183
	v_subrev_u32_e32 v190, 72, v202
	v_min_u32_e32 v190, s76, v190
	v_subrev_u32_e32 v191, 76, v202
	v_min_u32_e32 v191, s76, v191
	v_subrev_u32_e32 v192, 96, v202
	v_min_u32_e32 v192, s76, v192
	v_subrev_u32_e32 v193, 100, v202
	v_min_u32_e32 v193, s76, v193
	v_subrev_u32_e32 v194, 104, v202
	v_min_u32_e32 v194, s76, v194
	v_subrev_u32_e32 v195, 108, v202
	v_min_u32_e32 v195, s76, v195
	ds_read_b32 v174, v174
	ds_read_b32 v175, v175
	ds_read_b32 v176, v176
	ds_read_b32 v177, v177
	ds_read_b32 v178, v178
	ds_read_b32 v179, v179
	ds_read_b32 v180, v180
	ds_read_b32 v181, v181
	ds_read_b32 v182, v182
	ds_read_b32 v183, v183
	ds_read_b32 v190, v190
	ds_read_b32 v191, v191
	ds_read_b32 v192, v192
	ds_read_b32 v193, v193
	ds_read_b32 v194, v194
	ds_read_b32 v195, v195
	s_waitcnt lgkmcnt(0)
	v_add_f32_e32 v212, v212, v174
	v_add_f32_e32 v213, v213, v175
	v_add_f32_e32 v214, v214, v176
	v_add_f32_e32 v215, v215, v177
	v_add_f32_e32 v216, v216, v178
	v_add_f32_e32 v217, v217, v179
	v_add_f32_e32 v218, v218, v180
	v_add_f32_e32 v219, v219, v181
	v_add_f32_e32 v220, v220, v182
	v_add_f32_e32 v221, v221, v183
	v_add_f32_e32 v222, v222, v190
	v_add_f32_e32 v223, v223, v191
	v_add_f32_e32 v224, v224, v192
	v_add_f32_e32 v225, v225, v193
	v_add_f32_e32 v226, v226, v194
	v_add_f32_e32 v227, v227, v195
	s_mov_b32 s83, 0
	s_branch .Lat_bdone_2009

; DI void attn_block(const AttnItem& it, int key0, int qi, int hh, const bf16x8 (&bq)[4], LAS unsigned char* Kl, LAS unsigned char* Vl, unsigned kr, unsigned vr,
;                    float& mrun, float& lsum, f32x16& o0, f32x16& o1) {
;     ...
;     float mx = s[0];
; #pragma unroll
;     for (int r = 1; r < 16; ++r) mx = fmaxf(mx, s[r]);
;     mx = fmaxf(mx, __shfl_xor(mx, 32));
;     const float mnew = fmaxf(mrun, mx);
;     const float alpha = __builtin_amdgcn_exp2f(mrun - mnew);
;     mrun = mnew;
;     float rs = 0.f;
; #pragma unroll
;     for (int r = 0; r < 16; ++r) { s[r] = __builtin_amdgcn_exp2f(s[r] - mnew); rs += s[r]; }
;     lsum = lsum * alpha + rs;
; #pragma unroll
;     for (int r = 0; r < 16; ++r) { o0[r] *= alpha; o1[r] *= alpha; }
.Lat_bdone_2009:
	v_max3_f32 v196, v212, v213, v214
	v_max3_f32 v197, v215, v216, v217
	v_max3_f32 v196, v196, v218, v219
	v_max3_f32 v197, v197, v220, v221
	v_max3_f32 v196, v196, v222, v223
	v_max3_f32 v197, v197, v224, v225
	v_max3_f32 v196, v196, v226, v227
	v_max_f32_e32 v196, v196, v197
	v_mov_b32_e32 v197, v196
	s_nop 1
	v_permlane32_swap_b32_e32 v196, v197
	v_max_f32_e32 v196, v196, v197
	v_add_f32_e32 v196, s83, v196
	v_max_f32_e32 v196, v150, v196
	v_sub_f32_e32 v198, v150, v196
	v_exp_f32_e32 v198, v198
	v_sub_f32_e32 v199, s83, v196
	v_mov_b32_e32 v150, v196
	v_add_f32_e32 v212, v199, v212
	v_add_f32_e32 v213, v199, v213
	v_add_f32_e32 v214, v199, v214
	v_add_f32_e32 v215, v199, v215
	v_add_f32_e32 v216, v199, v216
	v_add_f32_e32 v217, v199, v217
	v_add_f32_e32 v218, v199, v218
	v_add_f32_e32 v219, v199, v219
	v_add_f32_e32 v220, v199, v220
	v_add_f32_e32 v221, v199, v221
	v_add_f32_e32 v222, v199, v222
	v_add_f32_e32 v223, v199, v223
	v_add_f32_e32 v224, v199, v224
	v_add_f32_e32 v225, v199, v225
	v_add_f32_e32 v226, v199, v226
	v_add_f32_e32 v227, v199, v227
	v_exp_f32_e32 v212, v212
	v_exp_f32_e32 v213, v213
	v_exp_f32_e32 v214, v214
	v_exp_f32_e32 v215, v215
	v_exp_f32_e32 v216, v216
	v_exp_f32_e32 v217, v217
	v_exp_f32_e32 v218, v218
	v_exp_f32_e32 v219, v219
	v_exp_f32_e32 v220, v220
	v_exp_f32_e32 v221, v221
	v_exp_f32_e32 v222, v222
	v_exp_f32_e32 v223, v223
	v_exp_f32_e32 v224, v224
	v_exp_f32_e32 v225, v225
	v_exp_f32_e32 v226, v226
	v_exp_f32_e32 v227, v227
	v_add_f32_e32 v200, v212, v213
	v_add_f32_e32 v201, v214, v215
	v_add_f32_e32 v200, v200, v216
	v_add_f32_e32 v201, v201, v217
	v_add_f32_e32 v200, v200, v218
	v_add_f32_e32 v201, v201, v219
	v_add_f32_e32 v200, v200, v220
	v_add_f32_e32 v201, v201, v221
	v_add_f32_e32 v200, v200, v222
	v_add_f32_e32 v201, v201, v223
	v_add_f32_e32 v200, v200, v224
	v_add_f32_e32 v201, v201, v225
	v_add_f32_e32 v200, v200, v226
	v_add_f32_e32 v201, v201, v227
	v_add_f32_e32 v200, v200, v201
	v_fma_f32 v152, v152, v198, v200
	v_mul_f32_e32 v32, v198, v32
	v_mul_f32_e32 v48, v198, v48
	v_mul_f32_e32 v33, v198, v33
	v_mul_f32_e32 v49, v198, v49
	v_mul_f32_e32 v34, v198, v34
	v_mul_f32_e32 v50, v198, v50
	v_mul_f32_e32 v35, v198, v35
	v_mul_f32_e32 v51, v198, v51
	v_mul_f32_e32 v36, v198, v36
	v_mul_f32_e32 v52, v198, v52
	v_mul_f32_e32 v37, v198, v37
	v_mul_f32_e32 v53, v198, v53
	v_mul_f32_e32 v38, v198, v38
	v_mul_f32_e32 v54, v198, v54
	v_mul_f32_e32 v39, v198, v39
	v_mul_f32_e32 v55, v198, v55
	v_mul_f32_e32 v40, v198, v40
	v_mul_f32_e32 v56, v198, v56
	v_mul_f32_e32 v41, v198, v41
	v_mul_f32_e32 v57, v198, v57
	v_mul_f32_e32 v42, v198, v42
	v_mul_f32_e32 v58, v198, v58
	v_mul_f32_e32 v43, v198, v43
	v_mul_f32_e32 v59, v198, v59
	v_mul_f32_e32 v44, v198, v44
	v_mul_f32_e32 v60, v198, v60
	v_mul_f32_e32 v45, v198, v45
	v_mul_f32_e32 v61, v198, v61
	v_mul_f32_e32 v46, v198, v46
	v_mul_f32_e32 v62, v198, v62
	v_mul_f32_e32 v47, v198, v47
	v_mul_f32_e32 v63, v198, v63
	v_cvt_pk_bf16_f32 v212, v212, v213
	v_cvt_pk_bf16_f32 v213, v214, v215
	v_cvt_pk_bf16_f32 v214, v216, v217
	v_cvt_pk_bf16_f32 v215, v218, v219
	v_cvt_pk_bf16_f32 v220, v220, v221
	v_cvt_pk_bf16_f32 v221, v222, v223
	v_cvt_pk_bf16_f32 v222, v224, v225
	v_cvt_pk_bf16_f32 v223, v226, v227
	s_cmp_lt_u32 s77, s65
	s_cbranch_scc1 .Lat_v12_2004
	s_cmp_lt_u32 s79, s65
	s_cbranch_scc1 .Lat_v8_2005
	s_waitcnt vmcnt(0)
	s_branch .Lat_vdone_2006
.Lat_v8_2005:
	s_waitcnt vmcnt(8)
	s_branch .Lat_vdone_2006

; #define LAS __attribute__((address_space(3)))
; DI unsigned pk2(float a, float b) { f32x2 v = {a, b}; bf2v r = __builtin_convertvector(v, bf2v); return __builtin_bit_cast(unsigned, r); }
; #define MFMA32(a, b, c) __builtin_amdgcn_mfma_f32_32x32x16_bf16((a), (b), (c), 0, 0, 0)
; DI void attn_block(const AttnItem& it, int key0, int qi, int hh, const bf16x8 (&bq)[4], LAS unsigned char* Kl, LAS unsigned char* Vl, unsigned kr, unsigned vr,
;                    float& mrun, float& lsum, f32x16& o0, f32x16& o1) {
;     ...
;     if (it.bias) {
;         const int d0 = it.qpos0 - key0;
;         if (d0 - 31 >= 128) {
;             const float bc = it.bias[256];
; #pragma unroll
;             for (int r = 0; r < 16; ++r) s[r] += bc;
;         } else {
; #pragma unroll
;             for (int r = 0; r < 16; ++r) {
;                 int d = d0 + qi - ((r & 3) + 8 * (r >> 2) + 4 * hh);
;                 d = d < -128 ? -128 : (d > 128 ? 128 : d);
;                 s[r] += it.bias[d + 128];
;             }
;         }
;     ...
;     for (int ks = 0; ks < 2; ++ks) {
;         u32x4 pw; pw.x = pk2(s[8 * ks], s[8 * ks + 1]); pw.y = pk2(s[8 * ks + 2], s[8 * ks + 3]); pw.z = pk2(s[8 * ks + 4], s[8 * ks + 5]); pw.w = pk2(s[8 * ks + 6], s[8 * ks + 7]);
;         const bf16x8 pb = __builtin_bit_cast(bf16x8, pw);
;         const u32x2 a00 = *(const LAS u32x2*)(Vl + vr + ks * 32), a01 = *(const LAS u32x2*)(Vl + vr + ks * 32 + 16);
;         const u32x2 a10 = *(const LAS u32x2*)(Vl + vr + 2560 + ks * 32), a11 = *(const LAS u32x2*)(Vl + vr + 2560 + ks * 32 + 16);
;         u32x4 a0; a0.x = a00.x; a0.y = a00.y; a0.z = a01.x; a0.w = a01.y;
;         u32x4 a1; a1.x = a10.x; a1.y = a10.y; a1.z = a11.x; a1.w = a11.y;
;         o0 = MFMA32(__builtin_bit_cast(bf16x8, a0), pb, o0);
;         o1 = MFMA32(__builtin_bit_cast(bf16x8, a1), pb, o1);
;     }
.Lat_vdone_2006:
	ds_read_b64 v[120:121], v205 offset:0
	ds_read_b64 v[122:123], v206 offset:0
	ds_read_b64 v[124:125], v205 offset:2048
	ds_read_b64 v[126:127], v206 offset:2048
	ds_read_b64 v[158:159], v207 offset:0
	ds_read_b64 v[160:161], v208 offset:0
	ds_read_b64 v[162:163], v207 offset:2048
	ds_read_b64 v[164:165], v208 offset:2048
	s_waitcnt lgkmcnt(0)
	s_cmp_lt_u32 s77, s65
	s_cbranch_scc0 .Lat_novd_2007
	s_add_i32 m0, s70, 0x1000
	s_nop 0
	global_load_lds_dwordx4 v248, s[54:55]
	s_add_i32 m0, s70, 0x1400
	s_nop 0
	global_load_lds_dwordx4 v249, s[54:55]
	s_add_i32 m0, s70, 0x1800
	s_nop 0
	global_load_lds_dwordx4 v250, s[54:55]
	s_add_i32 m0, s70, 0x1c00
	s_nop 0
	global_load_lds_dwordx4 v251, s[54:55]
	s_add_u32 s54, s54, 0x1000
	s_addc_u32 s55, s55, 0
.Lat_novd_2007:
	v_mfma_f32_32x32x16_bf16 v[32:47], v[120:123], v[212:215], v[32:47]
	v_mfma_f32_32x32x16_bf16 v[48:63], v[124:127], v[212:215], v[48:63]
	v_mfma_f32_32x32x16_bf16 v[32:47], v[158:161], v[220:223], v[32:47]
	v_mfma_f32_32x32x16_bf16 v[48:63], v[162:165], v[220:223], v[48:63]
	s_add_i32 s85, s66, 32
	s_cmpk_ge_i32 s85, 0x9f
	s_cbranch_scc1 .Lat_far_2010
	s_lshl_b32 s82, s85, 2
	s_add_i32 s82, s82, s67
	v_add_u32_e32 v202, s82, v167
	v_min_u32_e32 v174, s76, v202
	v_subrev_u32_e32 v175, 4, v202
	v_min_u32_e32 v175, s76, v175
	v_subrev_u32_e32 v176, 8, v202
	v_min_u32_e32 v176, s76, v176
	v_subrev_u32_e32 v177, 12, v202
	v_min_u32_e32 v177, s76, v177
	v_subrev_u32_e32 v178, 32, v202
	v_min_u32_e32 v178, s76, v178
	v_subrev_u32_e32 v179, 36, v202
	v_min_u32_e32 v179, s76, v179
	v_subrev_u32_e32 v180, 40, v202
	v_min_u32_e32 v180, s76, v180
	v_subrev_u32_e32 v181, 44, v202
	v_min_u32_e32 v181, s76, v181
	v_subrev_u32_e32 v182, 64, v202
	v_min_u32_e32 v182, s76, v182
	v_subrev_u32_e32 v183, 68, v202
	v_min_u32_e32 v183, s76, v183
	v_subrev_u32_e32 v190, 72, v202
	v_min_u32_e32 v190, s76, v190
	v_subrev_u32_e32 v191, 76, v202
	v_min_u32_e32 v191, s76, v191
	v_subrev_u32_e32 v192, 96, v202
	v_min_u32_e32 v192, s76, v192
	v_subrev_u32_e32 v193, 100, v202
	v_min_u32_e32 v193, s76, v193
	v_subrev_u32_e32 v194, 104, v202
	v_min_u32_e32 v194, s76, v194
	v_subrev_u32_e32 v195, 108, v202
	v_min_u32_e32 v195, s76, v195
	ds_read_b32 v174, v174
	ds_read_b32 v175, v175
	ds_read_b32 v176, v176
	ds_read_b32 v177, v177
	ds_read_b32 v178, v178
	ds_read_b32 v179, v179
	ds_read_b32 v180, v180
	ds_read_b32 v181, v181
	ds_read_b32 v182, v182
	ds_read_b32 v183, v183
	ds_read_b32 v190, v190
	ds_read_b32 v191, v191
	ds_read_b32 v192, v192
	ds_read_b32 v193, v193
	ds_read_b32 v194, v194
	ds_read_b32 v195, v195
	s_waitcnt lgkmcnt(0)
	v_add_f32_e32 v228, v228, v174
	v_add_f32_e32 v229, v229, v175
	v_add_f32_e32 v230, v230, v176
	v_add_f32_e32 v231, v231, v177
	v_add_f32_e32 v232, v232, v178
	v_add_f32_e32 v233, v233, v179
	v_add_f32_e32 v234, v234, v180
	v_add_f32_e32 v235, v235, v181
	v_add_f32_e32 v236, v236, v182
	v_add_f32_e32 v237, v237, v183
	v_add_f32_e32 v238, v238, v190
	v_add_f32_e32 v239, v239, v191
	v_add_f32_e32 v240, v240, v192
	v_add_f32_e32 v241, v241, v193
	v_add_f32_e32 v242, v242, v194
	v_add_f32_e32 v243, v243, v195
	s_mov_b32 s83, 0
	s_branch .Lat_bdone_2011

; #define LAS __attribute__((address_space(3)))
; DI unsigned pk2(float a, float b) { f32x2 v = {a, b}; bf2v r = __builtin_convertvector(v, bf2v); return __builtin_bit_cast(unsigned, r); }
; #define MFMA32(a, b, c) __builtin_amdgcn_mfma_f32_32x32x16_bf16((a), (b), (c), 0, 0, 0)
; DI void attn_block(const AttnItem& it, int key0, int qi, int hh, const bf16x8 (&bq)[4], LAS unsigned char* Kl, LAS unsigned char* Vl, unsigned kr, unsigned vr,
;                    float& mrun, float& lsum, f32x16& o0, f32x16& o1) {
;     ...
;     float mx = s[0];
; #pragma unroll
;     for (int r = 1; r < 16; ++r) mx = fmaxf(mx, s[r]);
;     mx = fmaxf(mx, __shfl_xor(mx, 32));
;     const float mnew = fmaxf(mrun, mx);
;     const float alpha = __builtin_amdgcn_exp2f(mrun - mnew);
;     mrun = mnew;
;     float rs = 0.f;
; #pragma unroll
;     for (int r = 0; r < 16; ++r) { s[r] = __builtin_amdgcn_exp2f(s[r] - mnew); rs += s[r]; }
;     lsum = lsum * alpha + rs;
; #pragma unroll
;     for (int r = 0; r < 16; ++r) { o0[r] *= alpha; o1[r] *= alpha; }
; #pragma unroll
;     for (int ks = 0; ks < 2; ++ks) {
;         u32x4 pw; pw.x = pk2(s[8 * ks], s[8 * ks + 1]); pw.y = pk2(s[8 * ks + 2], s[8 * ks + 3]); pw.z = pk2(s[8 * ks + 4], s[8 * ks + 5]); pw.w = pk2(s[8 * ks + 6], s[8 * ks + 7]);
;         const bf16x8 pb = __builtin_bit_cast(bf16x8, pw);
;         const u32x2 a00 = *(const LAS u32x2*)(Vl + vr + ks * 32), a01 = *(const LAS u32x2*)(Vl + vr + ks * 32 + 16);
;         const u32x2 a10 = *(const LAS u32x2*)(Vl + vr + 2560 + ks * 32), a11 = *(const LAS u32x2*)(Vl + vr + 2560 + ks * 32 + 16);
;         u32x4 a0; a0.x = a00.x; a0.y = a00.y; a0.z = a01.x; a0.w = a01.y;
;         u32x4 a1; a1.x = a10.x; a1.y = a10.y; a1.z = a11.x; a1.w = a11.y;
;         o0 = MFMA32(__builtin_bit_cast(bf16x8, a0), pb, o0);
;         o1 = MFMA32(__builtin_bit_cast(bf16x8, a1), pb, o1);
;     }
.Lat_bdone_2011:
	v_max3_f32 v196, v228, v229, v230
	v_max3_f32 v197, v231, v232, v233
	v_max3_f32 v196, v196, v234, v235
	v_max3_f32 v197, v197, v236, v237
	v_max3_f32 v196, v196, v238, v239
	v_max3_f32 v197, v197, v240, v241
	v_max3_f32 v196, v196, v242, v243
	v_max_f32_e32 v196, v196, v197
	v_mov_b32_e32 v197, v196
	s_nop 1
	v_permlane32_swap_b32_e32 v196, v197
	v_max_f32_e32 v196, v196, v197
	v_add_f32_e32 v196, s83, v196
	v_max_f32_e32 v196, v151, v196
	v_sub_f32_e32 v198, v151, v196
	v_exp_f32_e32 v198, v198
	v_sub_f32_e32 v199, s83, v196
	v_mov_b32_e32 v151, v196
	v_add_f32_e32 v228, v199, v228
	v_add_f32_e32 v229, v199, v229
	v_add_f32_e32 v230, v199, v230
	v_add_f32_e32 v231, v199, v231
	v_add_f32_e32 v232, v199, v232
	v_add_f32_e32 v233, v199, v233
	v_add_f32_e32 v234, v199, v234
	v_add_f32_e32 v235, v199, v235
	v_add_f32_e32 v236, v199, v236
	v_add_f32_e32 v237, v199, v237
	v_add_f32_e32 v238, v199, v238
	v_add_f32_e32 v239, v199, v239
	v_add_f32_e32 v240, v199, v240
	v_add_f32_e32 v241, v199, v241
	v_add_f32_e32 v242, v199, v242
	v_add_f32_e32 v243, v199, v243
	v_exp_f32_e32 v228, v228
	v_exp_f32_e32 v229, v229
	v_exp_f32_e32 v230, v230
	v_exp_f32_e32 v231, v231
	v_exp_f32_e32 v232, v232
	v_exp_f32_e32 v233, v233
	v_exp_f32_e32 v234, v234
	v_exp_f32_e32 v235, v235
	v_exp_f32_e32 v236, v236
	v_exp_f32_e32 v237, v237
	v_exp_f32_e32 v238, v238
	v_exp_f32_e32 v239, v239
	v_exp_f32_e32 v240, v240
	v_exp_f32_e32 v241, v241
	v_exp_f32_e32 v242, v242
	v_exp_f32_e32 v243, v243
	v_add_f32_e32 v200, v228, v229
	v_add_f32_e32 v201, v230, v231
	v_add_f32_e32 v200, v200, v232
	v_add_f32_e32 v201, v201, v233
	v_add_f32_e32 v200, v200, v234
	v_add_f32_e32 v201, v201, v235
	v_add_f32_e32 v200, v200, v236
	v_add_f32_e32 v201, v201, v237
	v_add_f32_e32 v200, v200, v238
	v_add_f32_e32 v201, v201, v239
	v_add_f32_e32 v200, v200, v240
	v_add_f32_e32 v201, v201, v241
	v_add_f32_e32 v200, v200, v242
	v_add_f32_e32 v201, v201, v243
	v_add_f32_e32 v200, v200, v201
	v_fma_f32 v157, v157, v198, v200
	v_mul_f32_e32 v64, v198, v64
	v_mul_f32_e32 v80, v198, v80
	v_mul_f32_e32 v65, v198, v65
	v_mul_f32_e32 v81, v198, v81
	v_mul_f32_e32 v66, v198, v66
	v_mul_f32_e32 v82, v198, v82
	v_mul_f32_e32 v67, v198, v67
	v_mul_f32_e32 v83, v198, v83
	v_mul_f32_e32 v68, v198, v68
	v_mul_f32_e32 v84, v198, v84
	v_mul_f32_e32 v69, v198, v69
	v_mul_f32_e32 v85, v198, v85
	v_mul_f32_e32 v70, v198, v70
	v_mul_f32_e32 v86, v198, v86
	v_mul_f32_e32 v71, v198, v71
	v_mul_f32_e32 v87, v198, v87
	v_mul_f32_e32 v72, v198, v72
	v_mul_f32_e32 v88, v198, v88
	v_mul_f32_e32 v73, v198, v73
	v_mul_f32_e32 v89, v198, v89
	v_mul_f32_e32 v74, v198, v74
	v_mul_f32_e32 v90, v198, v90
	v_mul_f32_e32 v75, v198, v75
	v_mul_f32_e32 v91, v198, v91
	v_mul_f32_e32 v76, v198, v76
	v_mul_f32_e32 v92, v198, v92
	v_mul_f32_e32 v77, v198, v77
	v_mul_f32_e32 v93, v198, v93
	v_mul_f32_e32 v78, v198, v78
	v_mul_f32_e32 v94, v198, v94
	v_mul_f32_e32 v79, v198, v79
	v_mul_f32_e32 v95, v198, v95
	v_cvt_pk_bf16_f32 v228, v228, v229
	v_cvt_pk_bf16_f32 v229, v230, v231
	v_cvt_pk_bf16_f32 v230, v232, v233
	v_cvt_pk_bf16_f32 v231, v234, v235
	v_cvt_pk_bf16_f32 v236, v236, v237
	v_cvt_pk_bf16_f32 v237, v238, v239
	v_cvt_pk_bf16_f32 v238, v240, v241
	v_cvt_pk_bf16_f32 v239, v242, v243
	s_nop 1
	v_mfma_f32_32x32x16_bf16 v[64:79], v[120:123], v[228:231], v[64:79]
	v_mfma_f32_32x32x16_bf16 v[80:95], v[124:127], v[228:231], v[80:95]
	v_mfma_f32_32x32x16_bf16 v[64:79], v[158:161], v[236:239], v[64:79]
	v_mfma_f32_32x32x16_bf16 v[80:95], v[162:165], v[236:239], v[80:95]
	s_add_i32 s71, s71, 1
	s_sub_i32 s66, s66, 32
	s_add_i32 s79, s71, 1
	s_add_i32 s77, s71, 2
	s_cmp_lt_u32 s79, s65
	s_cbranch_scc1 .Lat_k12_2012
	s_waitcnt vmcnt(4)
	s_branch .Lat_kdone_2013

; #define LAS __attribute__((address_space(3)))
; #define MFMA32(a, b, c) __builtin_amdgcn_mfma_f32_32x32x16_bf16((a), (b), (c), 0, 0, 0)
; #define ATT_LOAD(KR, VR, kb_) do { _Pragma("unroll") for (int i = 0; i < 4; ++i) { KR[i] = *(const u32x4*)(kg + (size_t)(32 * (kb_) + 8 * i) * it.kld); VR[i] = *(const u32x4*)(vg + (size_t)(16 * i) * it.vtld + 32 * (kb_)); } } while (0)
; #define ATT_STORE(KR, VR) do { _Pragma("unroll") for (int i = 0; i < 4; ++i) { *(LAS u32x4*)(Kl + kw + i * 1152) = KR[i]; *(LAS u32x4*)(Vl + vw + i * 1280) = VR[i]; } } while (0)
; DI void attn_block(const AttnItem& it, int key0, int qi, int hh, const bf16x8 (&bq)[4], LAS unsigned char* Kl, LAS unsigned char* Vl, unsigned kr, unsigned vr,
;                    float& mrun, float& lsum, f32x16& o0, f32x16& o1) {
;     ...
; #pragma unroll
;     for (int r = 0; r < 16; ++r) s[r] = 0.f;
; #pragma unroll
;     for (int kk = 0; kk < 4; ++kk) { const bf16x8 ak = *(const LAS bf16x8*)(Kl + kr + kk * 32); s = MFMA32(ak, bq[kk], s); }
; DI void attn_item(const AttnItem& it, LAS unsigned char* wl, int lane) {
;     ...
;     for (int kb = 0; kb < it.nkb; kb += 2) {
;         ATT_STORE(kA, vA);
;         if (kb + 2 < it.nkb) ATT_LOAD(kA, vA, kb + 2);
;         attn_block(it, 32 * kb, qi, hh, bq, Kl, Vl, kr, vr, mrun, lsum, o0, o1);
;         if (kb + 1 < it.nkb) {
;             ATT_STORE(kB, vB);
;             if (kb + 3 < it.nkb) ATT_LOAD(kB, vB, kb + 3);
.Lat_kdone_2013:
	ds_read_b128 v[96:99], v252 offset:8192
	ds_read_b128 v[100:103], v253 offset:8192
	ds_read_b128 v[104:107], v254 offset:8192
	ds_read_b128 v[116:119], v204 offset:8192
	s_waitcnt lgkmcnt(0)
	v_mfma_f32_32x32x16_bf16 v[212:227], v[96:99], v[0:3], 0
	v_mfma_f32_32x32x16_bf16 v[212:227], v[100:103], v[4:7], v[212:227]
	v_mfma_f32_32x32x16_bf16 v[212:227], v[104:107], v[8:11], v[212:227]
	v_mfma_f32_32x32x16_bf16 v[212:227], v[116:119], v[12:15], v[212:227]
	v_mfma_f32_32x32x16_bf16 v[228:243], v[96:99], v[16:19], 0
	v_mfma_f32_32x32x16_bf16 v[228:243], v[100:103], v[20:23], v[228:243]
	v_mfma_f32_32x32x16_bf16 v[228:243], v[104:107], v[24:27], v[228:243]
	v_mfma_f32_32x32x16_bf16 v[228:243], v[116:119], v[28:31], v[228:243]
	s_nop 3
	s_cmp_lt_u32 s77, s65
	s_cbranch_scc0 .Lat_nokd_2014
	s_add_i32 m0, s70, 0x2000
	s_nop 0
	global_load_lds_dwordx4 v244, s[52:53]
	s_add_i32 m0, s70, 0x2400
	s_nop 0
	global_load_lds_dwordx4 v245, s[52:53]
	s_add_i32 m0, s70, 0x2800
	s_nop 0
	global_load_lds_dwordx4 v246, s[52:53]
	s_add_i32 m0, s70, 0x2c00
	s_nop 0
	global_load_lds_dwordx4 v247, s[52:53]
	s_add_u32 s52, s52, s75
	s_addc_u32 s53, s53, 0

; #define LAS __attribute__((address_space(3)))
; DI unsigned pk2(float a, float b) { f32x2 v = {a, b}; bf2v r = __builtin_convertvector(v, bf2v); return __builtin_bit_cast(unsigned, r); }
; #define ATT_LOAD(KR, VR, kb_) do { _Pragma("unroll") for (int i = 0; i < 4; ++i) { KR[i] = *(const u32x4*)(kg + (size_t)(32 * (kb_) + 8 * i) * it.kld); VR[i] = *(const u32x4*)(vg + (size_t)(16 * i) * it.vtld + 32 * (kb_)); } } while (0)
; #define ATT_STORE(KR, VR) do { _Pragma("unroll") for (int i = 0; i < 4; ++i) { *(LAS u32x4*)(Kl + kw + i * 1152) = KR[i]; *(LAS u32x4*)(Vl + vw + i * 1280) = VR[i]; } } while (0)
; DI void attn_block(const AttnItem& it, int key0, int qi, int hh, const bf16x8 (&bq)[4], LAS unsigned char* Kl, LAS unsigned char* Vl, unsigned kr, unsigned vr,
;                    float& mrun, float& lsum, f32x16& o0, f32x16& o1) {
;     ...
;     for (int ks = 0; ks < 2; ++ks) {
;         u32x4 pw; pw.x = pk2(s[8 * ks], s[8 * ks + 1]); pw.y = pk2(s[8 * ks + 2], s[8 * ks + 3]); pw.z = pk2(s[8 * ks + 4], s[8 * ks + 5]); pw.w = pk2(s[8 * ks + 6], s[8 * ks + 7]);
;         const bf16x8 pb = __builtin_bit_cast(bf16x8, pw);
;         const u32x2 a00 = *(const LAS u32x2*)(Vl + vr + ks * 32), a01 = *(const LAS u32x2*)(Vl + vr + ks * 32 + 16);
;         const u32x2 a10 = *(const LAS u32x2*)(Vl + vr + 2560 + ks * 32), a11 = *(const LAS u32x2*)(Vl + vr + 2560 + ks * 32 + 16);
;         u32x4 a0; a0.x = a00.x; a0.y = a00.y; a0.z = a01.x; a0.w = a01.y;
;         u32x4 a1; a1.x = a10.x; a1.y = a10.y; a1.z = a11.x; a1.w = a11.y;
; DI void attn_item(const AttnItem& it, LAS unsigned char* wl, int lane) {
;     ...
;         if (kb + 1 < it.nkb) {
;             ATT_STORE(kB, vB);
;             if (kb + 3 < it.nkb) ATT_LOAD(kB, vB, kb + 3);
.Lat_vdone_2017:
	ds_read_b64 v[120:121], v205 offset:8192
	ds_read_b64 v[122:123], v206 offset:8192
	ds_read_b64 v[124:125], v205 offset:10240
	ds_read_b64 v[126:127], v206 offset:10240
	ds_read_b64 v[158:159], v207 offset:8192
	ds_read_b64 v[160:161], v208 offset:8192
	ds_read_b64 v[162:163], v207 offset:10240
	ds_read_b64 v[164:165], v208 offset:10240
	s_waitcnt lgkmcnt(0)
	s_cmp_lt_u32 s77, s65
	s_cbranch_scc0 .Lat_novd_2018
	s_add_i32 m0, s70, 0x3000
	s_nop 0
	global_load_lds_dwordx4 v248, s[54:55]
	s_add_i32 m0, s70, 0x3400
	s_nop 0
	global_load_lds_dwordx4 v249, s[54:55]
	s_add_i32 m0, s70, 0x3800
	s_nop 0
	global_load_lds_dwordx4 v250, s[54:55]
	s_add_i32 m0, s70, 0x3c00
	s_nop 0
	global_load_lds_dwordx4 v251, s[54:55]
	s_add_u32 s54, s54, 0x1000
	s_addc_u32 s55, s55, 0

; #define LAS __attribute__((address_space(3)))
; DI float bflo(unsigned w) { return __uint_as_float(w << 16); }
; DI void attn_block(const AttnItem& it, int key0, int qi, int hh, const bf16x8 (&bq)[4], LAS unsigned char* Kl, LAS unsigned char* Vl, unsigned kr, unsigned vr,
;                    float& mrun, float& lsum, f32x16& o0, f32x16& o1) {
;     ...
;     float mx = s[0];
; #pragma unroll
;     for (int r = 1; r < 16; ++r) mx = fmaxf(mx, s[r]);
;     mx = fmaxf(mx, __shfl_xor(mx, 32));
;     const float mnew = fmaxf(mrun, mx);
;     const float alpha = __builtin_amdgcn_exp2f(mrun - mnew);
;     mrun = mnew;
;     float rs = 0.f;
; #pragma unroll
;     for (int r = 0; r < 16; ++r) { s[r] = __builtin_amdgcn_exp2f(s[r] - mnew); rs += s[r]; }
;     lsum = lsum * alpha + rs;
; #pragma unroll
;     for (int r = 0; r < 16; ++r) { o0[r] *= alpha; o1[r] *= alpha; }
; #pragma unroll
;     for (int ks = 0; ks < 2; ++ks) {
;         u32x4 pw; pw.x = pk2(s[8 * ks], s[8 * ks + 1]); pw.y = pk2(s[8 * ks + 2], s[8 * ks + 3]); pw.z = pk2(s[8 * ks + 4], s[8 * ks + 5]); pw.w = pk2(s[8 * ks + 6], s[8 * ks + 7]);
;         const bf16x8 pb = __builtin_bit_cast(bf16x8, pw);
;         const u32x2 a00 = *(const LAS u32x2*)(Vl + vr + ks * 32), a01 = *(const LAS u32x2*)(Vl + vr + ks * 32 + 16);
;         const u32x2 a10 = *(const LAS u32x2*)(Vl + vr + 2560 + ks * 32), a11 = *(const LAS u32x2*)(Vl + vr + 2560 + ks * 32 + 16);
;         u32x4 a0; a0.x = a00.x; a0.y = a00.y; a0.z = a01.x; a0.w = a01.y;
;         u32x4 a1; a1.x = a10.x; a1.y = a10.y; a1.z = a11.x; a1.w = a11.y;
;         o0 = MFMA32(__builtin_bit_cast(bf16x8, a0), pb, o0);
;         o1 = MFMA32(__builtin_bit_cast(bf16x8, a1), pb, o1);
;     }
; DI void attn_item(const AttnItem& it, LAS unsigned char* wl, int lane) {
;     ...
;     lsum += __shfl_xor(lsum, 32);
;     const float inv = __fdividef(1.f, lsum);
;     if (qi < it.nq) {
;         bf16_t* zr = it.zo + (size_t)qi * it.zold + 4 * hh;
; #pragma unroll
;         for (int g = 0; g < 4; ++g) {
;             { const u32x2 z = *(const u32x2*)(zr + 8 * g); u32x2 w;
;               w.x = pk2(o0[4 * g] * inv * bflo(z.x), o0[4 * g + 1] * inv * bfhi(z.x)); w.y = pk2(o0[4 * g + 2] * inv * bflo(z.y), o0[4 * g + 3] * inv * bfhi(z.y));
;               *(u32x2*)(zr + 8 * g) = w; }
;             { const u32x2 z = *(const u32x2*)(zr + 32 + 8 * g); u32x2 w;
.Lat_bdone_2022:
	v_max3_f32 v196, v228, v229, v230
	v_max3_f32 v197, v231, v232, v233
	v_max3_f32 v196, v196, v234, v235
	v_max3_f32 v197, v197, v236, v237
	v_max3_f32 v196, v196, v238, v239
	v_max3_f32 v197, v197, v240, v241
	v_max3_f32 v196, v196, v242, v243
	v_max_f32_e32 v196, v196, v197
	v_mov_b32_e32 v197, v196
	s_nop 1
	v_permlane32_swap_b32_e32 v196, v197
	v_max_f32_e32 v196, v196, v197
	v_add_f32_e32 v196, s83, v196
	v_max_f32_e32 v196, v151, v196
	v_sub_f32_e32 v198, v151, v196
	v_exp_f32_e32 v198, v198
	v_sub_f32_e32 v199, s83, v196
	v_mov_b32_e32 v151, v196
	v_add_f32_e32 v228, v199, v228
	v_add_f32_e32 v229, v199, v229
	v_add_f32_e32 v230, v199, v230
	v_add_f32_e32 v231, v199, v231
	v_add_f32_e32 v232, v199, v232
	v_add_f32_e32 v233, v199, v233
	v_add_f32_e32 v234, v199, v234
	v_add_f32_e32 v235, v199, v235
	v_add_f32_e32 v236, v199, v236
	v_add_f32_e32 v237, v199, v237
	v_add_f32_e32 v238, v199, v238
	v_add_f32_e32 v239, v199, v239
	v_add_f32_e32 v240, v199, v240
	v_add_f32_e32 v241, v199, v241
	v_add_f32_e32 v242, v199, v242
	v_add_f32_e32 v243, v199, v243
	v_exp_f32_e32 v228, v228
	v_exp_f32_e32 v229, v229
	v_exp_f32_e32 v230, v230
	v_exp_f32_e32 v231, v231
	v_exp_f32_e32 v232, v232
	v_exp_f32_e32 v233, v233
	v_exp_f32_e32 v234, v234
	v_exp_f32_e32 v235, v235
	v_exp_f32_e32 v236, v236
	v_exp_f32_e32 v237, v237
	v_exp_f32_e32 v238, v238
	v_exp_f32_e32 v239, v239
	v_exp_f32_e32 v240, v240
	v_exp_f32_e32 v241, v241
	v_exp_f32_e32 v242, v242
	v_exp_f32_e32 v243, v243
	v_add_f32_e32 v200, v228, v229
	v_add_f32_e32 v201, v230, v231
	v_add_f32_e32 v200, v200, v232
	v_add_f32_e32 v201, v201, v233
	v_add_f32_e32 v200, v200, v234
	v_add_f32_e32 v201, v201, v235
	v_add_f32_e32 v200, v200, v236
	v_add_f32_e32 v201, v201, v237
	v_add_f32_e32 v200, v200, v238
	v_add_f32_e32 v201, v201, v239
	v_add_f32_e32 v200, v200, v240
	v_add_f32_e32 v201, v201, v241
	v_add_f32_e32 v200, v200, v242
	v_add_f32_e32 v201, v201, v243
	v_add_f32_e32 v200, v200, v201
	v_fma_f32 v157, v157, v198, v200
	v_mul_f32_e32 v64, v198, v64
	v_mul_f32_e32 v80, v198, v80
	v_mul_f32_e32 v65, v198, v65
	v_mul_f32_e32 v81, v198, v81
	v_mul_f32_e32 v66, v198, v66
	v_mul_f32_e32 v82, v198, v82
	v_mul_f32_e32 v67, v198, v67
	v_mul_f32_e32 v83, v198, v83
	v_mul_f32_e32 v68, v198, v68
	v_mul_f32_e32 v84, v198, v84
	v_mul_f32_e32 v69, v198, v69
	v_mul_f32_e32 v85, v198, v85
	v_mul_f32_e32 v70, v198, v70
	v_mul_f32_e32 v86, v198, v86
	v_mul_f32_e32 v71, v198, v71
	v_mul_f32_e32 v87, v198, v87
	v_mul_f32_e32 v72, v198, v72
	v_mul_f32_e32 v88, v198, v88
	v_mul_f32_e32 v73, v198, v73
	v_mul_f32_e32 v89, v198, v89
	v_mul_f32_e32 v74, v198, v74
	v_mul_f32_e32 v90, v198, v90
	v_mul_f32_e32 v75, v198, v75
	v_mul_f32_e32 v91, v198, v91
	v_mul_f32_e32 v76, v198, v76
	v_mul_f32_e32 v92, v198, v92
	v_mul_f32_e32 v77, v198, v77
	v_mul_f32_e32 v93, v198, v93
	v_mul_f32_e32 v78, v198, v78
	v_mul_f32_e32 v94, v198, v94
	v_mul_f32_e32 v79, v198, v79
	v_mul_f32_e32 v95, v198, v95
	v_cvt_pk_bf16_f32 v228, v228, v229
	v_cvt_pk_bf16_f32 v229, v230, v231
	v_cvt_pk_bf16_f32 v230, v232, v233
	v_cvt_pk_bf16_f32 v231, v234, v235
	v_cvt_pk_bf16_f32 v236, v236, v237
	v_cvt_pk_bf16_f32 v237, v238, v239
	v_cvt_pk_bf16_f32 v238, v240, v241
	v_cvt_pk_bf16_f32 v239, v242, v243
	s_nop 1
	v_mfma_f32_32x32x16_bf16 v[64:79], v[120:123], v[228:231], v[64:79]
	v_mfma_f32_32x32x16_bf16 v[80:95], v[124:127], v[228:231], v[80:95]
	v_mfma_f32_32x32x16_bf16 v[64:79], v[158:161], v[236:239], v[64:79]
	v_mfma_f32_32x32x16_bf16 v[80:95], v[162:165], v[236:239], v[80:95]
	s_add_i32 s71, s71, 1
	s_sub_i32 s66, s66, 32
	s_cmp_lt_u32 s71, s65
	s_cbranch_scc1 .Lat2_loop
	s_nop 7
	v_mov_b32_e32 v197, v152
	s_nop 1
	v_permlane32_swap_b32_e32 v152, v197
	v_add_f32_e32 v152, v152, v197
	v_rcp_f32_e32 v152, v152
	v_mov_b32_e32 v197, v157
	s_nop 1
	v_permlane32_swap_b32_e32 v157, v197
	v_add_f32_e32 v157, v157, v197
	v_rcp_f32_e32 v157, v157
	global_load_dwordx2 v[212:213], v168, s[56:57]
	global_load_dwordx2 v[214:215], v168, s[56:57] offset:16
	global_load_dwordx2 v[216:217], v168, s[56:57] offset:32
	global_load_dwordx2 v[218:219], v168, s[56:57] offset:48
	global_load_dwordx2 v[220:221], v168, s[56:57] offset:64
	global_load_dwordx2 v[222:223], v168, s[56:57] offset:80
	global_load_dwordx2 v[224:225], v168, s[56:57] offset:96
	global_load_dwordx2 v[226:227], v168, s[56:57] offset:112
	v_add_u32_e32 v168, 0x8000, v168
	global_load_dwordx2 v[228:229], v168, s[56:57]
	global_load_dwordx2 v[230:231], v168, s[56:57] offset:16
	global_load_dwordx2 v[232:233], v168, s[56:57] offset:32
	global_load_dwordx2 v[234:235], v168, s[56:57] offset:48
	global_load_dwordx2 v[236:237], v168, s[56:57] offset:64
	global_load_dwordx2 v[238:239], v168, s[56:57] offset:80
	global_load_dwordx2 v[240:241], v168, s[56:57] offset:96
	global_load_dwordx2 v[242:243], v168, s[56:57] offset:112
	v_subrev_u32_e32 v168, 0x8000, v168
	s_waitcnt vmcnt(15)
	v_mul_f32_e32 v32, v32, v152
	v_mul_f32_e32 v33, v33, v152
	v_mul_f32_e32 v34, v34, v152
	v_mul_f32_e32 v35, v35, v152
	v_lshlrev_b32_e32 v196, 16, v212
	v_and_b32_e32 v197, 0xffff0000, v212
	v_lshlrev_b32_e32 v198, 16, v213
	v_and_b32_e32 v199, 0xffff0000, v213
	v_mul_f32_e32 v32, v32, v196
	v_mul_f32_e32 v33, v33, v197
	v_mul_f32_e32 v34, v34, v198
	v_mul_f32_e32 v35, v35, v199
	v_cvt_pk_bf16_f32 v32, v32, v33
	v_cvt_pk_bf16_f32 v33, v34, v35
	global_store_dwordx2 v168, v[32:33], s[56:57]
	s_waitcnt vmcnt(15)
; DI unsigned pk2(float a, float b) { f32x2 v = {a, b}; bf2v r = __builtin_convertvector(v, bf2v); return __builtin_bit_cast(unsigned, r); }
; DI float bflo(unsigned w) { return __uint_as_float(w << 16); }
; DI float bfhi(unsigned w) { return __uint_as_float(w & 0xffff0000u); }
; DI void attn_item(const AttnItem& it, LAS unsigned char* wl, int lane) {
;     ...
;     if (qi < it.nq) {
;         bf16_t* zr = it.zo + (size_t)qi * it.zold + 4 * hh;
; #pragma unroll
;         for (int g = 0; g < 4; ++g) {
;             { const u32x2 z = *(const u32x2*)(zr + 8 * g); u32x2 w;
;               w.x = pk2(o0[4 * g] * inv * bflo(z.x), o0[4 * g + 1] * inv * bfhi(z.x)); w.y = pk2(o0[4 * g + 2] * inv * bflo(z.y), o0[4 * g + 3] * inv * bfhi(z.y));
;               *(u32x2*)(zr + 8 * g) = w; }
;             { const u32x2 z = *(const u32x2*)(zr + 32 + 8 * g); u32x2 w;
;               w.x = pk2(o1[4 * g] * inv * bflo(z.x), o1[4 * g + 1] * inv * bfhi(z.x)); w.y = pk2(o1[4 * g + 2] * inv * bflo(z.y), o1[4 * g + 3] * inv * bfhi(z.y));
;               *(u32x2*)(zr + 32 + 8 * g) = w; }
;         }
	v_mul_f32_e32 v36, v36, v152
	v_mul_f32_e32 v37, v37, v152
	v_mul_f32_e32 v38, v38, v152
	v_mul_f32_e32 v39, v39, v152
	v_lshlrev_b32_e32 v196, 16, v214
	v_and_b32_e32 v197, 0xffff0000, v214
	v_lshlrev_b32_e32 v198, 16, v215
	v_and_b32_e32 v199, 0xffff0000, v215
	v_mul_f32_e32 v36, v36, v196
	v_mul_f32_e32 v37, v37, v197
	v_mul_f32_e32 v38, v38, v198
	v_mul_f32_e32 v39, v39, v199
	v_cvt_pk_bf16_f32 v36, v36, v37
	v_cvt_pk_bf16_f32 v37, v38, v39
	global_store_dwordx2 v168, v[36:37], s[56:57] offset:16
	s_waitcnt vmcnt(15)
	v_mul_f32_e32 v40, v40, v152
	v_mul_f32_e32 v41, v41, v152
	v_mul_f32_e32 v42, v42, v152
	v_mul_f32_e32 v43, v43, v152
	v_lshlrev_b32_e32 v196, 16, v216
	v_and_b32_e32 v197, 0xffff0000, v216
	v_lshlrev_b32_e32 v198, 16, v217
	v_and_b32_e32 v199, 0xffff0000, v217
	v_mul_f32_e32 v40, v40, v196
	v_mul_f32_e32 v41, v41, v197
	v_mul_f32_e32 v42, v42, v198
	v_mul_f32_e32 v43, v43, v199
	v_cvt_pk_bf16_f32 v40, v40, v41
	v_cvt_pk_bf16_f32 v41, v42, v43
	global_store_dwordx2 v168, v[40:41], s[56:57] offset:32
	s_waitcnt vmcnt(15)
	v_mul_f32_e32 v44, v44, v152
	v_mul_f32_e32 v45, v45, v152
	v_mul_f32_e32 v46, v46, v152
	v_mul_f32_e32 v47, v47, v152
	v_lshlrev_b32_e32 v196, 16, v218
	v_and_b32_e32 v197, 0xffff0000, v218
	v_lshlrev_b32_e32 v198, 16, v219
	v_and_b32_e32 v199, 0xffff0000, v219
	v_mul_f32_e32 v44, v44, v196
	v_mul_f32_e32 v45, v45, v197
	v_mul_f32_e32 v46, v46, v198
	v_mul_f32_e32 v47, v47, v199
	v_cvt_pk_bf16_f32 v44, v44, v45
	v_cvt_pk_bf16_f32 v45, v46, v47
	global_store_dwordx2 v168, v[44:45], s[56:57] offset:48
	s_waitcnt vmcnt(15)
	v_mul_f32_e32 v48, v48, v152
	v_mul_f32_e32 v49, v49, v152
	v_mul_f32_e32 v50, v50, v152
	v_mul_f32_e32 v51, v51, v152
	v_lshlrev_b32_e32 v196, 16, v220
	v_and_b32_e32 v197, 0xffff0000, v220
	v_lshlrev_b32_e32 v198, 16, v221
	v_and_b32_e32 v199, 0xffff0000, v221
	v_mul_f32_e32 v48, v48, v196
	v_mul_f32_e32 v49, v49, v197
	v_mul_f32_e32 v50, v50, v198
	v_mul_f32_e32 v51, v51, v199
	v_cvt_pk_bf16_f32 v48, v48, v49
	v_cvt_pk_bf16_f32 v49, v50, v51
	global_store_dwordx2 v168, v[48:49], s[56:57] offset:64
	s_waitcnt vmcnt(15)
	v_mul_f32_e32 v52, v52, v152
	v_mul_f32_e32 v53, v53, v152
	v_mul_f32_e32 v54, v54, v152
	v_mul_f32_e32 v55, v55, v152
	v_lshlrev_b32_e32 v196, 16, v222
	v_and_b32_e32 v197, 0xffff0000, v222
	v_lshlrev_b32_e32 v198, 16, v223
	v_and_b32_e32 v199, 0xffff0000, v223
	v_mul_f32_e32 v52, v52, v196
	v_mul_f32_e32 v53, v53, v197
	v_mul_f32_e32 v54, v54, v198
	v_mul_f32_e32 v55, v55, v199
	v_cvt_pk_bf16_f32 v52, v52, v53
	v_cvt_pk_bf16_f32 v53, v54, v55
	global_store_dwordx2 v168, v[52:53], s[56:57] offset:80
	s_waitcnt vmcnt(15)
	v_mul_f32_e32 v56, v56, v152
	v_mul_f32_e32 v57, v57, v152
	v_mul_f32_e32 v58, v58, v152
	v_mul_f32_e32 v59, v59, v152
	v_lshlrev_b32_e32 v196, 16, v224
	v_and_b32_e32 v197, 0xffff0000, v224
	v_lshlrev_b32_e32 v198, 16, v225
	v_and_b32_e32 v199, 0xffff0000, v225
	v_mul_f32_e32 v56, v56, v196
	v_mul_f32_e32 v57, v57, v197
	v_mul_f32_e32 v58, v58, v198
	v_mul_f32_e32 v59, v59, v199
	v_cvt_pk_bf16_f32 v56, v56, v57
	v_cvt_pk_bf16_f32 v57, v58, v59
	global_store_dwordx2 v168, v[56:57], s[56:57] offset:96
	s_waitcnt vmcnt(15)
	v_mul_f32_e32 v60, v60, v152
	v_mul_f32_e32 v61, v61, v152
	v_mul_f32_e32 v62, v62, v152
	v_mul_f32_e32 v63, v63, v152
	v_lshlrev_b32_e32 v196, 16, v226
	v_and_b32_e32 v197, 0xffff0000, v226
	v_lshlrev_b32_e32 v198, 16, v227
	v_and_b32_e32 v199, 0xffff0000, v227
	v_mul_f32_e32 v60, v60, v196
	v_mul_f32_e32 v61, v61, v197
	v_mul_f32_e32 v62, v62, v198
	v_mul_f32_e32 v63, v63, v199
	v_cvt_pk_bf16_f32 v60, v60, v61
	v_cvt_pk_bf16_f32 v61, v62, v63
	global_store_dwordx2 v168, v[60:61], s[56:57] offset:112
	v_add_u32_e32 v168, 0x8000, v168
	s_waitcnt vmcnt(15)
; DI unsigned pk2(float a, float b) { f32x2 v = {a, b}; bf2v r = __builtin_convertvector(v, bf2v); return __builtin_bit_cast(unsigned, r); }
; DI float bflo(unsigned w) { return __uint_as_float(w << 16); }
; DI float bfhi(unsigned w) { return __uint_as_float(w & 0xffff0000u); }
; DI void attn_item(const AttnItem& it, LAS unsigned char* wl, int lane) {
;     ...
;     if (qi < it.nq) {
;         bf16_t* zr = it.zo + (size_t)qi * it.zold + 4 * hh;
; #pragma unroll
;         for (int g = 0; g < 4; ++g) {
;             { const u32x2 z = *(const u32x2*)(zr + 8 * g); u32x2 w;
;               w.x = pk2(o0[4 * g] * inv * bflo(z.x), o0[4 * g + 1] * inv * bfhi(z.x)); w.y = pk2(o0[4 * g + 2] * inv * bflo(z.y), o0[4 * g + 3] * inv * bfhi(z.y));
;               *(u32x2*)(zr + 8 * g) = w; }
;             { const u32x2 z = *(const u32x2*)(zr + 32 + 8 * g); u32x2 w;
;               w.x = pk2(o1[4 * g] * inv * bflo(z.x), o1[4 * g + 1] * inv * bfhi(z.x)); w.y = pk2(o1[4 * g + 2] * inv * bflo(z.y), o1[4 * g + 3] * inv * bfhi(z.y));
;               *(u32x2*)(zr + 32 + 8 * g) = w; }
;         }
;     }
	v_mul_f32_e32 v64, v64, v157
	v_mul_f32_e32 v65, v65, v157
	v_mul_f32_e32 v66, v66, v157
	v_mul_f32_e32 v67, v67, v157
	v_lshlrev_b32_e32 v196, 16, v228
	v_and_b32_e32 v197, 0xffff0000, v228
	v_lshlrev_b32_e32 v198, 16, v229
	v_and_b32_e32 v199, 0xffff0000, v229
	v_mul_f32_e32 v64, v64, v196
	v_mul_f32_e32 v65, v65, v197
	v_mul_f32_e32 v66, v66, v198
	v_mul_f32_e32 v67, v67, v199
	v_cvt_pk_bf16_f32 v64, v64, v65
	v_cvt_pk_bf16_f32 v65, v66, v67
	global_store_dwordx2 v168, v[64:65], s[56:57]
	s_waitcnt vmcnt(15)
	v_mul_f32_e32 v68, v68, v157
	v_mul_f32_e32 v69, v69, v157
	v_mul_f32_e32 v70, v70, v157
	v_mul_f32_e32 v71, v71, v157
	v_lshlrev_b32_e32 v196, 16, v230
	v_and_b32_e32 v197, 0xffff0000, v230
	v_lshlrev_b32_e32 v198, 16, v231
	v_and_b32_e32 v199, 0xffff0000, v231
	v_mul_f32_e32 v68, v68, v196
	v_mul_f32_e32 v69, v69, v197
	v_mul_f32_e32 v70, v70, v198
	v_mul_f32_e32 v71, v71, v199
	v_cvt_pk_bf16_f32 v68, v68, v69
	v_cvt_pk_bf16_f32 v69, v70, v71
	global_store_dwordx2 v168, v[68:69], s[56:57] offset:16
	s_waitcnt vmcnt(15)
	v_mul_f32_e32 v72, v72, v157
	v_mul_f32_e32 v73, v73, v157
	v_mul_f32_e32 v74, v74, v157
	v_mul_f32_e32 v75, v75, v157
	v_lshlrev_b32_e32 v196, 16, v232
	v_and_b32_e32 v197, 0xffff0000, v232
	v_lshlrev_b32_e32 v198, 16, v233
	v_and_b32_e32 v199, 0xffff0000, v233
	v_mul_f32_e32 v72, v72, v196
	v_mul_f32_e32 v73, v73, v197
	v_mul_f32_e32 v74, v74, v198
	v_mul_f32_e32 v75, v75, v199
	v_cvt_pk_bf16_f32 v72, v72, v73
	v_cvt_pk_bf16_f32 v73, v74, v75
	global_store_dwordx2 v168, v[72:73], s[56:57] offset:32
	s_waitcnt vmcnt(15)
	v_mul_f32_e32 v76, v76, v157
	v_mul_f32_e32 v77, v77, v157
	v_mul_f32_e32 v78, v78, v157
	v_mul_f32_e32 v79, v79, v157
	v_lshlrev_b32_e32 v196, 16, v234
	v_and_b32_e32 v197, 0xffff0000, v234
	v_lshlrev_b32_e32 v198, 16, v235
	v_and_b32_e32 v199, 0xffff0000, v235
	v_mul_f32_e32 v76, v76, v196
	v_mul_f32_e32 v77, v77, v197
	v_mul_f32_e32 v78, v78, v198
	v_mul_f32_e32 v79, v79, v199
	v_cvt_pk_bf16_f32 v76, v76, v77
	v_cvt_pk_bf16_f32 v77, v78, v79
	global_store_dwordx2 v168, v[76:77], s[56:57] offset:48
	s_waitcnt vmcnt(15)
	v_mul_f32_e32 v80, v80, v157
	v_mul_f32_e32 v81, v81, v157
	v_mul_f32_e32 v82, v82, v157
	v_mul_f32_e32 v83, v83, v157
	v_lshlrev_b32_e32 v196, 16, v236
	v_and_b32_e32 v197, 0xffff0000, v236
	v_lshlrev_b32_e32 v198, 16, v237
	v_and_b32_e32 v199, 0xffff0000, v237
	v_mul_f32_e32 v80, v80, v196
	v_mul_f32_e32 v81, v81, v197
	v_mul_f32_e32 v82, v82, v198
	v_mul_f32_e32 v83, v83, v199
	v_cvt_pk_bf16_f32 v80, v80, v81
	v_cvt_pk_bf16_f32 v81, v82, v83
	global_store_dwordx2 v168, v[80:81], s[56:57] offset:64
	s_waitcnt vmcnt(15)
	v_mul_f32_e32 v84, v84, v157
	v_mul_f32_e32 v85, v85, v157
	v_mul_f32_e32 v86, v86, v157
	v_mul_f32_e32 v87, v87, v157
	v_lshlrev_b32_e32 v196, 16, v238
	v_and_b32_e32 v197, 0xffff0000, v238
	v_lshlrev_b32_e32 v198, 16, v239
	v_and_b32_e32 v199, 0xffff0000, v239
	v_mul_f32_e32 v84, v84, v196
	v_mul_f32_e32 v85, v85, v197
	v_mul_f32_e32 v86, v86, v198
	v_mul_f32_e32 v87, v87, v199
	v_cvt_pk_bf16_f32 v84, v84, v85
	v_cvt_pk_bf16_f32 v85, v86, v87
	global_store_dwordx2 v168, v[84:85], s[56:57] offset:80
	s_waitcnt vmcnt(15)
	v_mul_f32_e32 v88, v88, v157
	v_mul_f32_e32 v89, v89, v157
	v_mul_f32_e32 v90, v90, v157
	v_mul_f32_e32 v91, v91, v157
	v_lshlrev_b32_e32 v196, 16, v240
	v_and_b32_e32 v197, 0xffff0000, v240
	v_lshlrev_b32_e32 v198, 16, v241
	v_and_b32_e32 v199, 0xffff0000, v241
	v_mul_f32_e32 v88, v88, v196
	v_mul_f32_e32 v89, v89, v197
	v_mul_f32_e32 v90, v90, v198
	v_mul_f32_e32 v91, v91, v199
	v_cvt_pk_bf16_f32 v88, v88, v89
	v_cvt_pk_bf16_f32 v89, v90, v91
	global_store_dwordx2 v168, v[88:89], s[56:57] offset:96
	s_waitcnt vmcnt(15)
	v_mul_f32_e32 v92, v92, v157
	v_mul_f32_e32 v93, v93, v157
	v_mul_f32_e32 v94, v94, v157
	v_mul_f32_e32 v95, v95, v157
	v_lshlrev_b32_e32 v196, 16, v242
	v_and_b32_e32 v197, 0xffff0000, v242
	v_lshlrev_b32_e32 v198, 16, v243
	v_and_b32_e32 v199, 0xffff0000, v243
	v_mul_f32_e32 v92, v92, v196
	v_mul_f32_e32 v93, v93, v197
	v_mul_f32_e32 v94, v94, v198
	v_mul_f32_e32 v95, v95, v199
	v_cvt_pk_bf16_f32 v92, v92, v93
	v_cvt_pk_bf16_f32 v93, v94, v95
	global_store_dwordx2 v168, v[92:93], s[56:57] offset:112
	s_branch .Lat_ret_band
